# v46 + static s_setprio 1 for waves 4-7 inside the GEMM K-loops (no per-segment flips)
# speedup vs baseline: 1.0111x; 1.0003x over previous
.LBB0_141:
	s_ashr_i32 s47, s46, 31
	s_lshl_b64 s[36:37], s[46:47], 19
	s_add_u32 s48, s20, s36
	s_addc_u32 s49, s34, s37
	s_and_b64 s[36:37], s[42:43], exec
	s_cselect_b32 s47, s49, s17
	s_cselect_b32 s78, s48, s16
	s_ashr_i32 s15, s14, 31
	s_lshl_b64 s[36:37], s[14:15], 19
	s_add_u32 s50, s39, s36
	s_addc_u32 s51, s40, s37
	s_and_b64 s[36:37], s[42:43], exec
	s_cselect_b32 s15, s51, s19
	s_cselect_b32 s79, s50, s18
	s_add_u32 s16, s16, 0x40080
	s_addc_u32 s17, s17, 0
	s_add_u32 s83, s18, 0x100
	v_mov_b32_e32 v2, 0
	s_addc_u32 s85, s19, 0
	s_mov_b32 s88, -2
	v_mov_b32_e32 v3, v2
	v_pk_mov_b32 v[4:5], v[2:3], v[2:3] op_sel:[0,1]
	v_pk_mov_b32 v[10:11], v[2:3], v[2:3] op_sel:[0,1]
	v_pk_mov_b32 v[12:13], v[2:3], v[2:3] op_sel:[0,1]
	v_pk_mov_b32 v[18:19], v[2:3], v[2:3] op_sel:[0,1]
	v_pk_mov_b32 v[20:21], v[2:3], v[2:3] op_sel:[0,1]
	v_pk_mov_b32 v[26:27], v[2:3], v[2:3] op_sel:[0,1]
	v_pk_mov_b32 v[28:29], v[2:3], v[2:3] op_sel:[0,1]
	v_pk_mov_b32 v[34:35], v[2:3], v[2:3] op_sel:[0,1]
	v_pk_mov_b32 v[36:37], v[2:3], v[2:3] op_sel:[0,1]
	v_pk_mov_b32 v[42:43], v[2:3], v[2:3] op_sel:[0,1]
	v_pk_mov_b32 v[44:45], v[2:3], v[2:3] op_sel:[0,1]
	v_pk_mov_b32 v[50:51], v[2:3], v[2:3] op_sel:[0,1]
	v_pk_mov_b32 v[52:53], v[2:3], v[2:3] op_sel:[0,1]
	v_pk_mov_b32 v[58:59], v[2:3], v[2:3] op_sel:[0,1]
	v_pk_mov_b32 v[60:61], v[2:3], v[2:3] op_sel:[0,1]
	v_pk_mov_b32 v[6:7], v[2:3], v[2:3] op_sel:[0,1]
	v_pk_mov_b32 v[8:9], v[2:3], v[2:3] op_sel:[0,1]
	v_pk_mov_b32 v[14:15], v[2:3], v[2:3] op_sel:[0,1]
	v_pk_mov_b32 v[16:17], v[2:3], v[2:3] op_sel:[0,1]
	v_pk_mov_b32 v[22:23], v[2:3], v[2:3] op_sel:[0,1]
	v_pk_mov_b32 v[24:25], v[2:3], v[2:3] op_sel:[0,1]
	v_pk_mov_b32 v[30:31], v[2:3], v[2:3] op_sel:[0,1]
	v_pk_mov_b32 v[32:33], v[2:3], v[2:3] op_sel:[0,1]
	v_pk_mov_b32 v[38:39], v[2:3], v[2:3] op_sel:[0,1]
	v_pk_mov_b32 v[40:41], v[2:3], v[2:3] op_sel:[0,1]
	v_pk_mov_b32 v[46:47], v[2:3], v[2:3] op_sel:[0,1]
	v_pk_mov_b32 v[48:49], v[2:3], v[2:3] op_sel:[0,1]
	v_pk_mov_b32 v[54:55], v[2:3], v[2:3] op_sel:[0,1]
	v_pk_mov_b32 v[56:57], v[2:3], v[2:3] op_sel:[0,1]
	v_pk_mov_b32 v[62:63], v[2:3], v[2:3] op_sel:[0,1]
	v_pk_mov_b32 v[64:65], v[2:3], v[2:3] op_sel:[0,1]
	v_pk_mov_b32 v[66:67], v[2:3], v[2:3] op_sel:[0,1]
	v_pk_mov_b32 v[68:69], v[2:3], v[2:3] op_sel:[0,1]
	v_pk_mov_b32 v[74:75], v[2:3], v[2:3] op_sel:[0,1]
	v_pk_mov_b32 v[76:77], v[2:3], v[2:3] op_sel:[0,1]
	v_pk_mov_b32 v[82:83], v[2:3], v[2:3] op_sel:[0,1]
	v_pk_mov_b32 v[84:85], v[2:3], v[2:3] op_sel:[0,1]
	v_pk_mov_b32 v[90:91], v[2:3], v[2:3] op_sel:[0,1]
	v_pk_mov_b32 v[92:93], v[2:3], v[2:3] op_sel:[0,1]
	v_pk_mov_b32 v[98:99], v[2:3], v[2:3] op_sel:[0,1]
	v_pk_mov_b32 v[100:101], v[2:3], v[2:3] op_sel:[0,1]
	v_pk_mov_b32 v[106:107], v[2:3], v[2:3] op_sel:[0,1]
	v_pk_mov_b32 v[108:109], v[2:3], v[2:3] op_sel:[0,1]
	v_pk_mov_b32 v[114:115], v[2:3], v[2:3] op_sel:[0,1]
	v_pk_mov_b32 v[116:117], v[2:3], v[2:3] op_sel:[0,1]
	v_pk_mov_b32 v[122:123], v[2:3], v[2:3] op_sel:[0,1]
	v_pk_mov_b32 v[124:125], v[2:3], v[2:3] op_sel:[0,1]
	v_pk_mov_b32 v[70:71], v[2:3], v[2:3] op_sel:[0,1]
	v_pk_mov_b32 v[72:73], v[2:3], v[2:3] op_sel:[0,1]
	v_pk_mov_b32 v[78:79], v[2:3], v[2:3] op_sel:[0,1]
	v_pk_mov_b32 v[80:81], v[2:3], v[2:3] op_sel:[0,1]
	v_pk_mov_b32 v[86:87], v[2:3], v[2:3] op_sel:[0,1]
	v_pk_mov_b32 v[88:89], v[2:3], v[2:3] op_sel:[0,1]
	v_pk_mov_b32 v[94:95], v[2:3], v[2:3] op_sel:[0,1]
	v_pk_mov_b32 v[96:97], v[2:3], v[2:3] op_sel:[0,1]
	v_pk_mov_b32 v[102:103], v[2:3], v[2:3] op_sel:[0,1]
	v_pk_mov_b32 v[104:105], v[2:3], v[2:3] op_sel:[0,1]
	v_pk_mov_b32 v[110:111], v[2:3], v[2:3] op_sel:[0,1]
	v_pk_mov_b32 v[112:113], v[2:3], v[2:3] op_sel:[0,1]
	v_pk_mov_b32 v[118:119], v[2:3], v[2:3] op_sel:[0,1]
	v_pk_mov_b32 v[120:121], v[2:3], v[2:3] op_sel:[0,1]
	v_pk_mov_b32 v[126:127], v[2:3], v[2:3] op_sel:[0,1]
	v_pk_mov_b32 v[128:129], v[2:3], v[2:3] op_sel:[0,1]
	v_readfirstlane_b32 s98, v208
	s_bitcmp1_b32 s98, 8
	s_cbranch_scc0 .Lsp_142
	s_setprio 1
.Lsp_142:
.LBB0_142:
	s_add_u32 s18, s16, 0xfffc0080
	s_addc_u32 s19, s17, -1
	s_add_i32 s28, 0, 0x10000
	s_cmp_eq_u32 s88, 12
	s_cselect_b32 s53, s47, s19
	s_cselect_b32 s52, s78, s18
	v_add_u32_e32 v140, s28, v143
	s_cselect_b32 s19, s15, s85
	s_cselect_b32 s18, s79, s83
	s_add_i32 s29, 0, 0x14000
	ds_read_b128 v[146:149], v140
	ds_read_b128 v[150:153], v140 offset:1024
	ds_read_b128 v[154:157], v140 offset:2048
	ds_read_b128 v[158:161], v140 offset:3072
	v_add_u32_e32 v140, s29, v143
	ds_read_b128 v[162:165], v140
	ds_read_b128 v[166:169], v140 offset:1024
	ds_read_b128 v[174:177], v140 offset:2048
	ds_read_b128 v[178:181], v140 offset:3072
	v_lshl_add_u64 v[140:141], s[16:17], 0, v[136:137]
	s_add_i32 m0, s54, 0xc000
	ds_read_b128 v[182:185], v145
	ds_read_b128 v[186:189], v145 offset:1024
	ds_read_b128 v[190:193], v145 offset:2048
	ds_read_b128 v[194:197], v145 offset:3072
	ds_read_b128 v[198:201], v145 offset:4096
	ds_read_b128 v[202:205], v145 offset:5120
	ds_read_b128 v[236:239], v145 offset:6144
	ds_read_b128 v[240:243], v145 offset:7168
	global_load_lds_dwordx4 v[140:141], off
	v_lshl_add_u64 v[140:141], s[16:17], 0, v[138:139]
	s_add_i32 m0, s54, 0xe000
	s_nop 0
	global_load_lds_dwordx4 v[140:141], off
	s_waitcnt vmcnt(8)
	s_waitcnt lgkmcnt(0)
	s_barrier
	s_waitcnt lgkmcnt(0)
	v_mfma_f32_16x16x32_bf16 v[126:129], v[146:149], v[182:185], v[126:129]
	v_mfma_f32_16x16x32_bf16 v[118:121], v[154:157], v[182:185], v[118:121]
	v_mfma_f32_16x16x32_bf16 v[110:113], v[146:149], v[190:193], v[110:113]
	v_mfma_f32_16x16x32_bf16 v[102:105], v[154:157], v[190:193], v[102:105]
	v_mfma_f32_16x16x32_bf16 v[94:97], v[146:149], v[198:201], v[94:97]
	v_mfma_f32_16x16x32_bf16 v[86:89], v[154:157], v[198:201], v[86:89]
	v_mfma_f32_16x16x32_bf16 v[78:81], v[146:149], v[236:239], v[78:81]
	v_mfma_f32_16x16x32_bf16 v[70:73], v[154:157], v[236:239], v[70:73]
	v_mfma_f32_16x16x32_bf16 v[126:129], v[150:153], v[186:189], v[126:129]
	v_mfma_f32_16x16x32_bf16 v[118:121], v[158:161], v[186:189], v[118:121]
	v_mfma_f32_16x16x32_bf16 v[110:113], v[150:153], v[194:197], v[110:113]
	v_mfma_f32_16x16x32_bf16 v[102:105], v[158:161], v[194:197], v[102:105]
	v_mfma_f32_16x16x32_bf16 v[94:97], v[150:153], v[202:205], v[94:97]
	v_mfma_f32_16x16x32_bf16 v[86:89], v[158:161], v[202:205], v[86:89]
	v_mfma_f32_16x16x32_bf16 v[78:81], v[150:153], v[240:243], v[78:81]
	v_mfma_f32_16x16x32_bf16 v[70:73], v[158:161], v[240:243], v[70:73]
	v_mfma_f32_16x16x32_bf16 v[122:125], v[162:165], v[182:185], v[122:125]
	v_mfma_f32_16x16x32_bf16 v[114:117], v[174:177], v[182:185], v[114:117]
	v_mfma_f32_16x16x32_bf16 v[106:109], v[162:165], v[190:193], v[106:109]
	v_mfma_f32_16x16x32_bf16 v[98:101], v[174:177], v[190:193], v[98:101]
	v_mfma_f32_16x16x32_bf16 v[90:93], v[162:165], v[198:201], v[90:93]
	v_mfma_f32_16x16x32_bf16 v[82:85], v[174:177], v[198:201], v[82:85]
	v_mfma_f32_16x16x32_bf16 v[74:77], v[162:165], v[236:239], v[74:77]
	v_mfma_f32_16x16x32_bf16 v[66:69], v[174:177], v[236:239], v[66:69]
	v_mfma_f32_16x16x32_bf16 v[122:125], v[166:169], v[186:189], v[122:125]
	v_mfma_f32_16x16x32_bf16 v[114:117], v[178:181], v[186:189], v[114:117]
	v_mfma_f32_16x16x32_bf16 v[106:109], v[166:169], v[194:197], v[106:109]
	v_mfma_f32_16x16x32_bf16 v[98:101], v[178:181], v[194:197], v[98:101]
	v_mfma_f32_16x16x32_bf16 v[90:93], v[166:169], v[202:205], v[90:93]
	v_mfma_f32_16x16x32_bf16 v[82:85], v[178:181], v[202:205], v[82:85]
	v_mfma_f32_16x16x32_bf16 v[74:77], v[166:169], v[240:243], v[74:77]
	v_mfma_f32_16x16x32_bf16 v[66:69], v[178:181], v[240:243], v[66:69]
	s_barrier
	s_add_i32 s28, s28, s41
	v_lshl_add_u64 v[140:141], s[18:19], 0, v[0:1]
	s_mov_b32 m0, s28
	ds_read_b128 v[182:185], v145 offset:16384
	ds_read_b128 v[186:189], v145 offset:17408
	ds_read_b128 v[190:193], v145 offset:18432
	ds_read_b128 v[194:197], v145 offset:19456
	ds_read_b128 v[198:201], v145 offset:20480
	ds_read_b128 v[202:205], v145 offset:21504
	ds_read_b128 v[236:239], v145 offset:22528
	ds_read_b128 v[240:243], v145 offset:23552
	global_load_lds_dwordx4 v[140:141], off
	s_add_i32 m0, s28, 0x2000
	s_add_u32 s36, s18, 0x40000
	v_lshl_add_u64 v[206:207], s[18:19], 0, v[130:131]
	s_addc_u32 s37, s19, 0
	s_add_i32 s28, s29, s41
	global_load_lds_dwordx4 v[206:207], off
	v_lshl_add_u64 v[228:229], s[36:37], 0, v[0:1]
	s_mov_b32 m0, s28
	v_lshl_add_u64 v[244:245], s[52:53], 0, v[132:133]
	global_load_lds_dwordx4 v[228:229], off
	v_lshl_add_u64 v[228:229], s[36:37], 0, v[130:131]
	s_add_i32 m0, s28, 0x2000
	s_nop 0
	global_load_lds_dwordx4 v[228:229], off
	v_lshl_add_u64 v[228:229], s[52:53], 0, v[134:135]
	s_mov_b32 m0, s54
	s_nop 0
	global_load_lds_dwordx4 v[228:229], off
	s_mov_b32 m0, s55
	s_nop 0
	global_load_lds_dwordx4 v[244:245], off
	s_waitcnt vmcnt(8)
	s_waitcnt lgkmcnt(0)
	s_barrier
	s_waitcnt lgkmcnt(0)
	v_mfma_f32_16x16x32_bf16 v[62:65], v[146:149], v[182:185], v[62:65]
	v_mfma_f32_16x16x32_bf16 v[54:57], v[154:157], v[182:185], v[54:57]
	v_mfma_f32_16x16x32_bf16 v[46:49], v[146:149], v[190:193], v[46:49]
	v_mfma_f32_16x16x32_bf16 v[38:41], v[154:157], v[190:193], v[38:41]
	v_mfma_f32_16x16x32_bf16 v[30:33], v[146:149], v[198:201], v[30:33]
	v_mfma_f32_16x16x32_bf16 v[22:25], v[154:157], v[198:201], v[22:25]
	v_mfma_f32_16x16x32_bf16 v[14:17], v[146:149], v[236:239], v[14:17]
	v_mfma_f32_16x16x32_bf16 v[6:9], v[154:157], v[236:239], v[6:9]
	v_mfma_f32_16x16x32_bf16 v[62:65], v[150:153], v[186:189], v[62:65]
	v_mfma_f32_16x16x32_bf16 v[54:57], v[158:161], v[186:189], v[54:57]
	v_mfma_f32_16x16x32_bf16 v[46:49], v[150:153], v[194:197], v[46:49]
	v_mfma_f32_16x16x32_bf16 v[38:41], v[158:161], v[194:197], v[38:41]
	v_mfma_f32_16x16x32_bf16 v[30:33], v[150:153], v[202:205], v[30:33]
	v_mfma_f32_16x16x32_bf16 v[22:25], v[158:161], v[202:205], v[22:25]
	v_mfma_f32_16x16x32_bf16 v[14:17], v[150:153], v[240:243], v[14:17]
	v_mfma_f32_16x16x32_bf16 v[6:9], v[158:161], v[240:243], v[6:9]
	v_mfma_f32_16x16x32_bf16 v[58:61], v[162:165], v[182:185], v[58:61]
	v_mfma_f32_16x16x32_bf16 v[50:53], v[174:177], v[182:185], v[50:53]
	v_mfma_f32_16x16x32_bf16 v[42:45], v[162:165], v[190:193], v[42:45]
	v_mfma_f32_16x16x32_bf16 v[34:37], v[174:177], v[190:193], v[34:37]
	v_mfma_f32_16x16x32_bf16 v[26:29], v[162:165], v[198:201], v[26:29]
	v_mfma_f32_16x16x32_bf16 v[18:21], v[174:177], v[198:201], v[18:21]
	v_mfma_f32_16x16x32_bf16 v[10:13], v[162:165], v[236:239], v[10:13]
	v_mfma_f32_16x16x32_bf16 v[2:5], v[174:177], v[236:239], v[2:5]
	v_mfma_f32_16x16x32_bf16 v[58:61], v[166:169], v[186:189], v[58:61]
	v_mfma_f32_16x16x32_bf16 v[50:53], v[178:181], v[186:189], v[50:53]
	v_mfma_f32_16x16x32_bf16 v[42:45], v[166:169], v[194:197], v[42:45]
	v_mfma_f32_16x16x32_bf16 v[34:37], v[178:181], v[194:197], v[34:37]
	v_mfma_f32_16x16x32_bf16 v[26:29], v[166:169], v[202:205], v[26:29]
	v_mfma_f32_16x16x32_bf16 v[18:21], v[178:181], v[202:205], v[18:21]
	v_mfma_f32_16x16x32_bf16 v[10:13], v[166:169], v[240:243], v[10:13]
	v_mfma_f32_16x16x32_bf16 v[2:5], v[178:181], v[240:243], v[2:5]
	s_barrier
	s_add_i32 s28, 0, 0x18000
	s_add_i32 s29, 0, 0x1c000
	v_add_u32_e32 v158, s28, v143
	v_add_u32_e32 v178, s29, v143
	ds_read_b128 v[146:149], v158
	ds_read_b128 v[150:153], v158 offset:1024
	ds_read_b128 v[154:157], v158 offset:2048
	ds_read_b128 v[158:161], v158 offset:3072
	ds_read_b128 v[162:165], v178
	ds_read_b128 v[166:169], v178 offset:1024
	ds_read_b128 v[174:177], v178 offset:2048
	ds_read_b128 v[178:181], v178 offset:3072
	s_add_u32 s36, s52, 0x40000
	s_addc_u32 s37, s53, 0
	s_mov_b32 m0, s70
	v_lshl_add_u64 v[246:247], s[36:37], 0, v[134:135]
	ds_read_b128 v[182:185], v145 offset:32768
	ds_read_b128 v[186:189], v145 offset:33792
	ds_read_b128 v[190:193], v145 offset:34816
	ds_read_b128 v[194:197], v145 offset:35840
	ds_read_b128 v[198:201], v145 offset:36864
	ds_read_b128 v[202:205], v145 offset:37888
	ds_read_b128 v[236:239], v145 offset:38912
	ds_read_b128 v[240:243], v145 offset:39936
	global_load_lds_dwordx4 v[246:247], off
	v_lshl_add_u64 v[246:247], s[36:37], 0, v[132:133]
	s_mov_b32 m0, s71
	s_nop 0
	global_load_lds_dwordx4 v[246:247], off
	s_waitcnt vmcnt(8)
	s_waitcnt lgkmcnt(0)
	s_barrier
	s_waitcnt lgkmcnt(0)
	v_mfma_f32_16x16x32_bf16 v[126:129], v[146:149], v[182:185], v[126:129]
	v_mfma_f32_16x16x32_bf16 v[118:121], v[154:157], v[182:185], v[118:121]
	v_mfma_f32_16x16x32_bf16 v[110:113], v[146:149], v[190:193], v[110:113]
	v_mfma_f32_16x16x32_bf16 v[102:105], v[154:157], v[190:193], v[102:105]
	v_mfma_f32_16x16x32_bf16 v[94:97], v[146:149], v[198:201], v[94:97]
	v_mfma_f32_16x16x32_bf16 v[86:89], v[154:157], v[198:201], v[86:89]
	v_mfma_f32_16x16x32_bf16 v[78:81], v[146:149], v[236:239], v[78:81]
	v_mfma_f32_16x16x32_bf16 v[70:73], v[154:157], v[236:239], v[70:73]
	v_mfma_f32_16x16x32_bf16 v[126:129], v[150:153], v[186:189], v[126:129]
	v_mfma_f32_16x16x32_bf16 v[118:121], v[158:161], v[186:189], v[118:121]
	v_mfma_f32_16x16x32_bf16 v[110:113], v[150:153], v[194:197], v[110:113]
	v_mfma_f32_16x16x32_bf16 v[102:105], v[158:161], v[194:197], v[102:105]
	v_mfma_f32_16x16x32_bf16 v[94:97], v[150:153], v[202:205], v[94:97]
	v_mfma_f32_16x16x32_bf16 v[86:89], v[158:161], v[202:205], v[86:89]
	v_mfma_f32_16x16x32_bf16 v[78:81], v[150:153], v[240:243], v[78:81]
	v_mfma_f32_16x16x32_bf16 v[70:73], v[158:161], v[240:243], v[70:73]
	v_mfma_f32_16x16x32_bf16 v[122:125], v[162:165], v[182:185], v[122:125]
	v_mfma_f32_16x16x32_bf16 v[114:117], v[174:177], v[182:185], v[114:117]
	v_mfma_f32_16x16x32_bf16 v[106:109], v[162:165], v[190:193], v[106:109]
	v_mfma_f32_16x16x32_bf16 v[98:101], v[174:177], v[190:193], v[98:101]
	v_mfma_f32_16x16x32_bf16 v[90:93], v[162:165], v[198:201], v[90:93]
	v_mfma_f32_16x16x32_bf16 v[82:85], v[174:177], v[198:201], v[82:85]
	v_mfma_f32_16x16x32_bf16 v[74:77], v[162:165], v[236:239], v[74:77]
	v_mfma_f32_16x16x32_bf16 v[66:69], v[174:177], v[236:239], v[66:69]
	v_mfma_f32_16x16x32_bf16 v[122:125], v[166:169], v[186:189], v[122:125]
	v_mfma_f32_16x16x32_bf16 v[114:117], v[178:181], v[186:189], v[114:117]
	v_mfma_f32_16x16x32_bf16 v[106:109], v[166:169], v[194:197], v[106:109]
	v_mfma_f32_16x16x32_bf16 v[98:101], v[178:181], v[194:197], v[98:101]
	v_mfma_f32_16x16x32_bf16 v[90:93], v[166:169], v[202:205], v[90:93]
	v_mfma_f32_16x16x32_bf16 v[82:85], v[178:181], v[202:205], v[82:85]
	v_mfma_f32_16x16x32_bf16 v[74:77], v[166:169], v[240:243], v[74:77]
	v_mfma_f32_16x16x32_bf16 v[66:69], v[178:181], v[240:243], v[66:69]
	s_barrier
	s_add_i32 s28, s28, s41
	v_lshl_add_u64 v[140:141], v[140:141], 0, s[4:5]
	s_mov_b32 m0, s28
	ds_read_b128 v[182:185], v145 offset:49152
	ds_read_b128 v[186:189], v145 offset:50176
	ds_read_b128 v[190:193], v145 offset:51200
	ds_read_b128 v[194:197], v145 offset:52224
	ds_read_b128 v[198:201], v145 offset:53248
	ds_read_b128 v[202:205], v145 offset:54272
	ds_read_b128 v[236:239], v145 offset:55296
	ds_read_b128 v[240:243], v145 offset:56320
	global_load_lds_dwordx4 v[140:141], off
	s_add_i32 m0, s28, 0x2000
	s_add_u32 s18, s18, 0x40080
	v_lshl_add_u64 v[140:141], v[206:207], 0, s[4:5]
	s_addc_u32 s19, s19, 0
	s_add_i32 s28, s29, s41
	global_load_lds_dwordx4 v[140:141], off
	v_lshl_add_u64 v[140:141], s[18:19], 0, v[0:1]
	s_mov_b32 m0, s28
	s_nop 0
	global_load_lds_dwordx4 v[140:141], off
	v_lshl_add_u64 v[140:141], s[18:19], 0, v[130:131]
	s_add_i32 m0, s28, 0x2000
	s_nop 0
	global_load_lds_dwordx4 v[140:141], off
	v_lshl_add_u64 v[140:141], v[228:229], 0, s[4:5]
	s_mov_b32 m0, s74
	s_nop 0
	global_load_lds_dwordx4 v[140:141], off
	v_lshl_add_u64 v[140:141], v[244:245], 0, s[4:5]
	s_mov_b32 m0, s75
	s_nop 0
	global_load_lds_dwordx4 v[140:141], off
	s_waitcnt vmcnt(8)
	s_waitcnt lgkmcnt(0)
	s_barrier
	s_waitcnt lgkmcnt(0)
	v_mfma_f32_16x16x32_bf16 v[62:65], v[146:149], v[182:185], v[62:65]
	v_mfma_f32_16x16x32_bf16 v[54:57], v[154:157], v[182:185], v[54:57]
	v_mfma_f32_16x16x32_bf16 v[46:49], v[146:149], v[190:193], v[46:49]
	v_mfma_f32_16x16x32_bf16 v[38:41], v[154:157], v[190:193], v[38:41]
	v_mfma_f32_16x16x32_bf16 v[30:33], v[146:149], v[198:201], v[30:33]
	v_mfma_f32_16x16x32_bf16 v[22:25], v[154:157], v[198:201], v[22:25]
	v_mfma_f32_16x16x32_bf16 v[14:17], v[146:149], v[236:239], v[14:17]
	v_mfma_f32_16x16x32_bf16 v[6:9], v[154:157], v[236:239], v[6:9]
	v_mfma_f32_16x16x32_bf16 v[62:65], v[150:153], v[186:189], v[62:65]
	v_mfma_f32_16x16x32_bf16 v[54:57], v[158:161], v[186:189], v[54:57]
	v_mfma_f32_16x16x32_bf16 v[46:49], v[150:153], v[194:197], v[46:49]
	v_mfma_f32_16x16x32_bf16 v[38:41], v[158:161], v[194:197], v[38:41]
	v_mfma_f32_16x16x32_bf16 v[30:33], v[150:153], v[202:205], v[30:33]
	v_mfma_f32_16x16x32_bf16 v[22:25], v[158:161], v[202:205], v[22:25]
	v_mfma_f32_16x16x32_bf16 v[14:17], v[150:153], v[240:243], v[14:17]
	v_mfma_f32_16x16x32_bf16 v[6:9], v[158:161], v[240:243], v[6:9]
	v_mfma_f32_16x16x32_bf16 v[58:61], v[162:165], v[182:185], v[58:61]
	v_mfma_f32_16x16x32_bf16 v[50:53], v[174:177], v[182:185], v[50:53]
	v_mfma_f32_16x16x32_bf16 v[42:45], v[162:165], v[190:193], v[42:45]
	v_mfma_f32_16x16x32_bf16 v[34:37], v[174:177], v[190:193], v[34:37]
	v_mfma_f32_16x16x32_bf16 v[26:29], v[162:165], v[198:201], v[26:29]
	v_mfma_f32_16x16x32_bf16 v[18:21], v[174:177], v[198:201], v[18:21]
	v_mfma_f32_16x16x32_bf16 v[10:13], v[162:165], v[236:239], v[10:13]
	v_mfma_f32_16x16x32_bf16 v[2:5], v[174:177], v[236:239], v[2:5]
	v_mfma_f32_16x16x32_bf16 v[58:61], v[166:169], v[186:189], v[58:61]
	v_mfma_f32_16x16x32_bf16 v[50:53], v[178:181], v[186:189], v[50:53]
	v_mfma_f32_16x16x32_bf16 v[42:45], v[166:169], v[194:197], v[42:45]
	v_mfma_f32_16x16x32_bf16 v[34:37], v[178:181], v[194:197], v[34:37]
	v_mfma_f32_16x16x32_bf16 v[26:29], v[166:169], v[202:205], v[26:29]
	v_mfma_f32_16x16x32_bf16 v[18:21], v[178:181], v[202:205], v[18:21]
	v_mfma_f32_16x16x32_bf16 v[10:13], v[166:169], v[240:243], v[10:13]
	v_mfma_f32_16x16x32_bf16 v[2:5], v[178:181], v[240:243], v[2:5]
	s_barrier
	s_add_i32 s88, s88, 2
	s_add_u32 s16, s16, 0x100
	s_addc_u32 s17, s17, 0
	s_add_u32 s83, s83, 0x100
	s_addc_u32 s85, s85, 0
	s_cmp_gt_u32 s88, 13
	s_cbranch_scc0 .LBB0_142
	s_setprio 0
	s_and_b64 vcc, exec, s[12:13]
	s_cbranch_vccz .LBB0_145
	s_barrier

.LBB0_193:
	s_add_u32 s10, s10, 0x80
	s_addc_u32 s11, s11, 0
	s_add_u32 s14, s12, 0x100
	v_mov_b32_e32 v2, 0
	s_addc_u32 s15, s13, 0
	s_mov_b32 s12, 0
	v_mov_b32_e32 v3, v2
	v_pk_mov_b32 v[4:5], v[2:3], v[2:3] op_sel:[0,1]
	v_pk_mov_b32 v[6:7], v[2:3], v[2:3] op_sel:[0,1]
	v_pk_mov_b32 v[8:9], v[2:3], v[2:3] op_sel:[0,1]
	v_pk_mov_b32 v[18:19], v[2:3], v[2:3] op_sel:[0,1]
	v_pk_mov_b32 v[20:21], v[2:3], v[2:3] op_sel:[0,1]
	v_pk_mov_b32 v[22:23], v[2:3], v[2:3] op_sel:[0,1]
	v_pk_mov_b32 v[24:25], v[2:3], v[2:3] op_sel:[0,1]
	v_pk_mov_b32 v[34:35], v[2:3], v[2:3] op_sel:[0,1]
	v_pk_mov_b32 v[36:37], v[2:3], v[2:3] op_sel:[0,1]
	v_pk_mov_b32 v[38:39], v[2:3], v[2:3] op_sel:[0,1]
	v_pk_mov_b32 v[40:41], v[2:3], v[2:3] op_sel:[0,1]
	v_pk_mov_b32 v[50:51], v[2:3], v[2:3] op_sel:[0,1]
	v_pk_mov_b32 v[52:53], v[2:3], v[2:3] op_sel:[0,1]
	v_pk_mov_b32 v[54:55], v[2:3], v[2:3] op_sel:[0,1]
	v_pk_mov_b32 v[56:57], v[2:3], v[2:3] op_sel:[0,1]
	v_pk_mov_b32 v[10:11], v[2:3], v[2:3] op_sel:[0,1]
	v_pk_mov_b32 v[12:13], v[2:3], v[2:3] op_sel:[0,1]
	v_pk_mov_b32 v[14:15], v[2:3], v[2:3] op_sel:[0,1]
	v_pk_mov_b32 v[16:17], v[2:3], v[2:3] op_sel:[0,1]
	s_waitcnt vmcnt(0)
	v_pk_mov_b32 v[26:27], v[2:3], v[2:3] op_sel:[0,1]
	v_pk_mov_b32 v[28:29], v[2:3], v[2:3] op_sel:[0,1]
	v_pk_mov_b32 v[30:31], v[2:3], v[2:3] op_sel:[0,1]
	v_pk_mov_b32 v[32:33], v[2:3], v[2:3] op_sel:[0,1]
	v_pk_mov_b32 v[42:43], v[2:3], v[2:3] op_sel:[0,1]
	v_pk_mov_b32 v[44:45], v[2:3], v[2:3] op_sel:[0,1]
	v_pk_mov_b32 v[46:47], v[2:3], v[2:3] op_sel:[0,1]
	v_pk_mov_b32 v[48:49], v[2:3], v[2:3] op_sel:[0,1]
	v_pk_mov_b32 v[58:59], v[2:3], v[2:3] op_sel:[0,1]
	v_pk_mov_b32 v[60:61], v[2:3], v[2:3] op_sel:[0,1]
	v_pk_mov_b32 v[62:63], v[2:3], v[2:3] op_sel:[0,1]
	v_pk_mov_b32 v[64:65], v[2:3], v[2:3] op_sel:[0,1]
	v_pk_mov_b32 v[66:67], v[2:3], v[2:3] op_sel:[0,1]
	v_pk_mov_b32 v[68:69], v[2:3], v[2:3] op_sel:[0,1]
	v_pk_mov_b32 v[70:71], v[2:3], v[2:3] op_sel:[0,1]
	v_pk_mov_b32 v[72:73], v[2:3], v[2:3] op_sel:[0,1]
	v_pk_mov_b32 v[82:83], v[2:3], v[2:3] op_sel:[0,1]
	v_pk_mov_b32 v[84:85], v[2:3], v[2:3] op_sel:[0,1]
	v_pk_mov_b32 v[86:87], v[2:3], v[2:3] op_sel:[0,1]
	v_pk_mov_b32 v[88:89], v[2:3], v[2:3] op_sel:[0,1]
	v_pk_mov_b32 v[98:99], v[2:3], v[2:3] op_sel:[0,1]
	v_pk_mov_b32 v[100:101], v[2:3], v[2:3] op_sel:[0,1]
	v_pk_mov_b32 v[102:103], v[2:3], v[2:3] op_sel:[0,1]
	v_pk_mov_b32 v[104:105], v[2:3], v[2:3] op_sel:[0,1]
	v_pk_mov_b32 v[130:131], v[2:3], v[2:3] op_sel:[0,1]
	v_pk_mov_b32 v[132:133], v[2:3], v[2:3] op_sel:[0,1]
	v_pk_mov_b32 v[134:135], v[2:3], v[2:3] op_sel:[0,1]
	v_pk_mov_b32 v[136:137], v[2:3], v[2:3] op_sel:[0,1]
	v_pk_mov_b32 v[74:75], v[2:3], v[2:3] op_sel:[0,1]
	v_pk_mov_b32 v[76:77], v[2:3], v[2:3] op_sel:[0,1]
	v_pk_mov_b32 v[78:79], v[2:3], v[2:3] op_sel:[0,1]
	v_pk_mov_b32 v[80:81], v[2:3], v[2:3] op_sel:[0,1]
	v_pk_mov_b32 v[90:91], v[2:3], v[2:3] op_sel:[0,1]
	v_pk_mov_b32 v[92:93], v[2:3], v[2:3] op_sel:[0,1]
	v_pk_mov_b32 v[94:95], v[2:3], v[2:3] op_sel:[0,1]
	v_pk_mov_b32 v[96:97], v[2:3], v[2:3] op_sel:[0,1]
	v_pk_mov_b32 v[106:107], v[2:3], v[2:3] op_sel:[0,1]
	v_pk_mov_b32 v[108:109], v[2:3], v[2:3] op_sel:[0,1]
	v_pk_mov_b32 v[110:111], v[2:3], v[2:3] op_sel:[0,1]
	v_pk_mov_b32 v[112:113], v[2:3], v[2:3] op_sel:[0,1]
	v_pk_mov_b32 v[138:139], v[2:3], v[2:3] op_sel:[0,1]
	v_pk_mov_b32 v[140:141], v[2:3], v[2:3] op_sel:[0,1]
	v_pk_mov_b32 v[142:143], v[2:3], v[2:3] op_sel:[0,1]
	v_pk_mov_b32 v[144:145], v[2:3], v[2:3] op_sel:[0,1]
	v_readfirstlane_b32 s98, v208
	s_bitcmp1_b32 s98, 8
	s_cbranch_scc0 .Lsp_194
	s_setprio 1
.Lsp_194:
.LBB0_194:
	s_add_i32 vcc_lo, s12, 2
	s_add_u32 s36, s10, 0x80
	s_addc_u32 s13, s11, 0
	s_add_i32 vcc_hi, 0, 0x10000
	s_cmp_eq_u32 s94, s12
	s_cselect_b32 s13, s45, s13
	s_cselect_b32 s12, s44, s36
	s_cselect_b32 s37, s79, s15
	s_cselect_b32 s36, s78, s14
	s_add_i32 s8, 0, 0x14000
	v_add_u32_e32 v126, vcc_hi, v197
	v_add_u32_e32 v158, s8, v197
	ds_read_b128 v[114:117], v126
	ds_read_b128 v[118:121], v126 offset:1024
	ds_read_b128 v[122:125], v126 offset:2048
	ds_read_b128 v[126:129], v126 offset:3072
	ds_read_b128 v[146:149], v158
	ds_read_b128 v[150:153], v158 offset:1024
	ds_read_b128 v[154:157], v158 offset:2048
	ds_read_b128 v[158:161], v158 offset:3072
	v_lshl_add_u64 v[240:241], s[10:11], 0, v[180:181]
	s_add_i32 m0, s18, 0xc000
	ds_read_b128 v[162:165], v199
	ds_read_b128 v[166:169], v199 offset:1024
	ds_read_b128 v[184:187], v199 offset:2048
	ds_read_b128 v[188:191], v199 offset:3072
	ds_read_b128 v[192:195], v199 offset:4096
	ds_read_b128 v[200:203], v199 offset:5120
	ds_read_b128 v[204:207], v199 offset:6144
	ds_read_b128 v[236:239], v199 offset:7168
	global_load_lds_dwordx4 v[240:241], off
	v_lshl_add_u64 v[240:241], s[10:11], 0, v[182:183]
	s_add_i32 m0, s18, 0xe000
	s_nop 0
	global_load_lds_dwordx4 v[240:241], off
	s_waitcnt vmcnt(8)
	s_waitcnt lgkmcnt(0)
	s_barrier
	s_waitcnt lgkmcnt(0)
	v_mfma_f32_16x16x32_bf16 v[142:145], v[114:117], v[162:165], v[142:145]
	v_mfma_f32_16x16x32_bf16 v[138:141], v[122:125], v[162:165], v[138:141]
	v_mfma_f32_16x16x32_bf16 v[110:113], v[114:117], v[184:187], v[110:113]
	v_mfma_f32_16x16x32_bf16 v[106:109], v[122:125], v[184:187], v[106:109]
	v_mfma_f32_16x16x32_bf16 v[94:97], v[114:117], v[192:195], v[94:97]
	v_mfma_f32_16x16x32_bf16 v[90:93], v[122:125], v[192:195], v[90:93]
	v_mfma_f32_16x16x32_bf16 v[78:81], v[114:117], v[204:207], v[78:81]
	v_mfma_f32_16x16x32_bf16 v[74:77], v[122:125], v[204:207], v[74:77]
	v_mfma_f32_16x16x32_bf16 v[142:145], v[118:121], v[166:169], v[142:145]
	v_mfma_f32_16x16x32_bf16 v[138:141], v[126:129], v[166:169], v[138:141]
	v_mfma_f32_16x16x32_bf16 v[110:113], v[118:121], v[188:191], v[110:113]
	v_mfma_f32_16x16x32_bf16 v[106:109], v[126:129], v[188:191], v[106:109]
	v_mfma_f32_16x16x32_bf16 v[94:97], v[118:121], v[200:203], v[94:97]
	v_mfma_f32_16x16x32_bf16 v[90:93], v[126:129], v[200:203], v[90:93]
	v_mfma_f32_16x16x32_bf16 v[78:81], v[118:121], v[236:239], v[78:81]
	v_mfma_f32_16x16x32_bf16 v[74:77], v[126:129], v[236:239], v[74:77]
	v_mfma_f32_16x16x32_bf16 v[134:137], v[146:149], v[162:165], v[134:137]
	v_mfma_f32_16x16x32_bf16 v[130:133], v[154:157], v[162:165], v[130:133]
	v_mfma_f32_16x16x32_bf16 v[102:105], v[146:149], v[184:187], v[102:105]
	v_mfma_f32_16x16x32_bf16 v[98:101], v[154:157], v[184:187], v[98:101]
	v_mfma_f32_16x16x32_bf16 v[86:89], v[146:149], v[192:195], v[86:89]
	v_mfma_f32_16x16x32_bf16 v[82:85], v[154:157], v[192:195], v[82:85]
	v_mfma_f32_16x16x32_bf16 v[70:73], v[146:149], v[204:207], v[70:73]
	v_mfma_f32_16x16x32_bf16 v[66:69], v[154:157], v[204:207], v[66:69]
	v_mfma_f32_16x16x32_bf16 v[134:137], v[150:153], v[166:169], v[134:137]
	v_mfma_f32_16x16x32_bf16 v[130:133], v[158:161], v[166:169], v[130:133]
	v_mfma_f32_16x16x32_bf16 v[102:105], v[150:153], v[188:191], v[102:105]
	v_mfma_f32_16x16x32_bf16 v[98:101], v[158:161], v[188:191], v[98:101]
	v_mfma_f32_16x16x32_bf16 v[86:89], v[150:153], v[200:203], v[86:89]
	v_mfma_f32_16x16x32_bf16 v[82:85], v[158:161], v[200:203], v[82:85]
	v_mfma_f32_16x16x32_bf16 v[70:73], v[150:153], v[236:239], v[70:73]
	v_mfma_f32_16x16x32_bf16 v[66:69], v[158:161], v[236:239], v[66:69]
	s_barrier
	s_add_i32 s9, vcc_hi, s17
	v_lshl_add_u64 v[240:241], s[36:37], 0, v[0:1]
	s_mov_b32 m0, s9
	ds_read_b128 v[162:165], v199 offset:16384
	ds_read_b128 v[166:169], v199 offset:17408
	ds_read_b128 v[184:187], v199 offset:18432
	ds_read_b128 v[188:191], v199 offset:19456
	ds_read_b128 v[192:195], v199 offset:20480
	ds_read_b128 v[200:203], v199 offset:21504
	ds_read_b128 v[204:207], v199 offset:22528
	ds_read_b128 v[236:239], v199 offset:23552
	global_load_lds_dwordx4 v[240:241], off
	s_add_i32 m0, s9, 0x2000
	v_lshl_add_u64 v[242:243], s[36:37], 0, v[174:175]
	s_add_u32 s36, s36, s20
	s_addc_u32 s37, s37, 0
	s_add_i32 s8, s8, s17
	global_load_lds_dwordx4 v[242:243], off
	v_lshl_add_u64 v[244:245], s[36:37], 0, v[0:1]
	s_mov_b32 m0, s8
	v_lshl_add_u64 v[246:247], s[36:37], 0, v[174:175]
	global_load_lds_dwordx4 v[244:245], off
	s_add_i32 m0, s8, 0x2000
	v_lshl_add_u64 v[248:249], s[12:13], 0, v[178:179]
	global_load_lds_dwordx4 v[246:247], off
	s_mov_b32 m0, s18
	v_lshl_add_u64 v[250:251], s[12:13], 0, v[176:177]
	global_load_lds_dwordx4 v[248:249], off
	s_mov_b32 m0, s19
	s_nop 0
	global_load_lds_dwordx4 v[250:251], off
	s_waitcnt vmcnt(8)
	s_waitcnt lgkmcnt(0)
	s_barrier
	s_waitcnt lgkmcnt(0)
	v_mfma_f32_16x16x32_bf16 v[62:65], v[114:117], v[162:165], v[62:65]
	v_mfma_f32_16x16x32_bf16 v[58:61], v[122:125], v[162:165], v[58:61]
	v_mfma_f32_16x16x32_bf16 v[46:49], v[114:117], v[184:187], v[46:49]
	v_mfma_f32_16x16x32_bf16 v[42:45], v[122:125], v[184:187], v[42:45]
	v_mfma_f32_16x16x32_bf16 v[30:33], v[114:117], v[192:195], v[30:33]
	v_mfma_f32_16x16x32_bf16 v[26:29], v[122:125], v[192:195], v[26:29]
	v_mfma_f32_16x16x32_bf16 v[14:17], v[114:117], v[204:207], v[14:17]
	v_mfma_f32_16x16x32_bf16 v[10:13], v[122:125], v[204:207], v[10:13]
	v_mfma_f32_16x16x32_bf16 v[62:65], v[118:121], v[166:169], v[62:65]
	v_mfma_f32_16x16x32_bf16 v[58:61], v[126:129], v[166:169], v[58:61]
	v_mfma_f32_16x16x32_bf16 v[46:49], v[118:121], v[188:191], v[46:49]
	v_mfma_f32_16x16x32_bf16 v[42:45], v[126:129], v[188:191], v[42:45]
	v_mfma_f32_16x16x32_bf16 v[30:33], v[118:121], v[200:203], v[30:33]
	v_mfma_f32_16x16x32_bf16 v[26:29], v[126:129], v[200:203], v[26:29]
	v_mfma_f32_16x16x32_bf16 v[14:17], v[118:121], v[236:239], v[14:17]
	v_mfma_f32_16x16x32_bf16 v[10:13], v[126:129], v[236:239], v[10:13]
	v_mfma_f32_16x16x32_bf16 v[54:57], v[146:149], v[162:165], v[54:57]
	v_mfma_f32_16x16x32_bf16 v[50:53], v[154:157], v[162:165], v[50:53]
	v_mfma_f32_16x16x32_bf16 v[38:41], v[146:149], v[184:187], v[38:41]
	v_mfma_f32_16x16x32_bf16 v[34:37], v[154:157], v[184:187], v[34:37]
	v_mfma_f32_16x16x32_bf16 v[22:25], v[146:149], v[192:195], v[22:25]
	v_mfma_f32_16x16x32_bf16 v[18:21], v[154:157], v[192:195], v[18:21]
	v_mfma_f32_16x16x32_bf16 v[6:9], v[146:149], v[204:207], v[6:9]
	v_mfma_f32_16x16x32_bf16 v[2:5], v[154:157], v[204:207], v[2:5]
	v_mfma_f32_16x16x32_bf16 v[54:57], v[150:153], v[166:169], v[54:57]
	v_mfma_f32_16x16x32_bf16 v[50:53], v[158:161], v[166:169], v[50:53]
	v_mfma_f32_16x16x32_bf16 v[38:41], v[150:153], v[188:191], v[38:41]
	v_mfma_f32_16x16x32_bf16 v[34:37], v[158:161], v[188:191], v[34:37]
	v_mfma_f32_16x16x32_bf16 v[22:25], v[150:153], v[200:203], v[22:25]
	v_mfma_f32_16x16x32_bf16 v[18:21], v[158:161], v[200:203], v[18:21]
	v_mfma_f32_16x16x32_bf16 v[6:9], v[150:153], v[236:239], v[6:9]
	v_mfma_f32_16x16x32_bf16 v[2:5], v[158:161], v[236:239], v[2:5]
	s_barrier
	s_add_i32 s8, 0, 0x18000
	s_add_i32 s9, 0, 0x1c000
	v_add_u32_e32 v126, s8, v197
	v_add_u32_e32 v158, s9, v197
	ds_read_b128 v[114:117], v126
	ds_read_b128 v[118:121], v126 offset:1024
	ds_read_b128 v[122:125], v126 offset:2048
	ds_read_b128 v[126:129], v126 offset:3072
	ds_read_b128 v[146:149], v158
	ds_read_b128 v[150:153], v158 offset:1024
	ds_read_b128 v[154:157], v158 offset:2048
	ds_read_b128 v[158:161], v158 offset:3072
	s_add_u32 s12, s12, s20
	s_addc_u32 s13, s13, 0
	s_mov_b32 m0, s70
	v_lshl_add_u64 v[228:229], s[12:13], 0, v[178:179]
	ds_read_b128 v[162:165], v199 offset:32768
	ds_read_b128 v[166:169], v199 offset:33792
	ds_read_b128 v[184:187], v199 offset:34816
	ds_read_b128 v[188:191], v199 offset:35840
	ds_read_b128 v[192:195], v199 offset:36864
	ds_read_b128 v[200:203], v199 offset:37888
	ds_read_b128 v[204:207], v199 offset:38912
	ds_read_b128 v[236:239], v199 offset:39936
	global_load_lds_dwordx4 v[228:229], off
	v_lshl_add_u64 v[228:229], s[12:13], 0, v[176:177]
	s_mov_b32 m0, s71
	s_nop 0
	global_load_lds_dwordx4 v[228:229], off
	s_waitcnt vmcnt(8)
	s_waitcnt lgkmcnt(0)
	s_barrier
	s_waitcnt lgkmcnt(0)
	v_mfma_f32_16x16x32_bf16 v[142:145], v[114:117], v[162:165], v[142:145]
	v_mfma_f32_16x16x32_bf16 v[138:141], v[122:125], v[162:165], v[138:141]
	v_mfma_f32_16x16x32_bf16 v[110:113], v[114:117], v[184:187], v[110:113]
	v_mfma_f32_16x16x32_bf16 v[106:109], v[122:125], v[184:187], v[106:109]
	v_mfma_f32_16x16x32_bf16 v[94:97], v[114:117], v[192:195], v[94:97]
	v_mfma_f32_16x16x32_bf16 v[90:93], v[122:125], v[192:195], v[90:93]
	v_mfma_f32_16x16x32_bf16 v[78:81], v[114:117], v[204:207], v[78:81]
	v_mfma_f32_16x16x32_bf16 v[74:77], v[122:125], v[204:207], v[74:77]
	v_mfma_f32_16x16x32_bf16 v[142:145], v[118:121], v[166:169], v[142:145]
	v_mfma_f32_16x16x32_bf16 v[138:141], v[126:129], v[166:169], v[138:141]
	v_mfma_f32_16x16x32_bf16 v[110:113], v[118:121], v[188:191], v[110:113]
	v_mfma_f32_16x16x32_bf16 v[106:109], v[126:129], v[188:191], v[106:109]
	v_mfma_f32_16x16x32_bf16 v[94:97], v[118:121], v[200:203], v[94:97]
	v_mfma_f32_16x16x32_bf16 v[90:93], v[126:129], v[200:203], v[90:93]
	v_mfma_f32_16x16x32_bf16 v[78:81], v[118:121], v[236:239], v[78:81]
	v_mfma_f32_16x16x32_bf16 v[74:77], v[126:129], v[236:239], v[74:77]
	v_mfma_f32_16x16x32_bf16 v[134:137], v[146:149], v[162:165], v[134:137]
	v_mfma_f32_16x16x32_bf16 v[130:133], v[154:157], v[162:165], v[130:133]
	v_mfma_f32_16x16x32_bf16 v[102:105], v[146:149], v[184:187], v[102:105]
	v_mfma_f32_16x16x32_bf16 v[98:101], v[154:157], v[184:187], v[98:101]
	v_mfma_f32_16x16x32_bf16 v[86:89], v[146:149], v[192:195], v[86:89]
	v_mfma_f32_16x16x32_bf16 v[82:85], v[154:157], v[192:195], v[82:85]
	v_mfma_f32_16x16x32_bf16 v[70:73], v[146:149], v[204:207], v[70:73]
	v_mfma_f32_16x16x32_bf16 v[66:69], v[154:157], v[204:207], v[66:69]
	v_mfma_f32_16x16x32_bf16 v[134:137], v[150:153], v[166:169], v[134:137]
	v_mfma_f32_16x16x32_bf16 v[130:133], v[158:161], v[166:169], v[130:133]
	v_mfma_f32_16x16x32_bf16 v[102:105], v[150:153], v[188:191], v[102:105]
	v_mfma_f32_16x16x32_bf16 v[98:101], v[158:161], v[188:191], v[98:101]
	v_mfma_f32_16x16x32_bf16 v[86:89], v[150:153], v[200:203], v[86:89]
	v_mfma_f32_16x16x32_bf16 v[82:85], v[158:161], v[200:203], v[82:85]
	v_mfma_f32_16x16x32_bf16 v[70:73], v[150:153], v[236:239], v[70:73]
	v_mfma_f32_16x16x32_bf16 v[66:69], v[158:161], v[236:239], v[66:69]
	s_barrier
	s_add_i32 s8, s8, s17
	v_lshl_add_u64 v[228:229], v[240:241], 0, s[4:5]
	s_mov_b32 m0, s8
	ds_read_b128 v[162:165], v199 offset:49152
	ds_read_b128 v[166:169], v199 offset:50176
	ds_read_b128 v[184:187], v199 offset:51200
	ds_read_b128 v[188:191], v199 offset:52224
	ds_read_b128 v[192:195], v199 offset:53248
	ds_read_b128 v[200:203], v199 offset:54272
	ds_read_b128 v[204:207], v199 offset:55296
	ds_read_b128 v[236:239], v199 offset:56320
	global_load_lds_dwordx4 v[228:229], off
	v_lshl_add_u64 v[228:229], v[242:243], 0, s[4:5]
	s_add_i32 m0, s8, 0x2000
	s_add_i32 s8, s9, s17
	global_load_lds_dwordx4 v[228:229], off
	v_lshl_add_u64 v[228:229], v[244:245], 0, s[4:5]
	s_mov_b32 m0, s8
	s_nop 0
	global_load_lds_dwordx4 v[228:229], off
	v_lshl_add_u64 v[228:229], v[246:247], 0, s[4:5]
	s_add_i32 m0, s8, 0x2000
	s_nop 0
	global_load_lds_dwordx4 v[228:229], off
	v_lshl_add_u64 v[228:229], v[248:249], 0, s[4:5]
	s_mov_b32 m0, s88
	s_nop 0
	global_load_lds_dwordx4 v[228:229], off
	v_lshl_add_u64 v[228:229], v[250:251], 0, s[4:5]
	s_mov_b32 m0, s89
	s_nop 0
	global_load_lds_dwordx4 v[228:229], off
	s_waitcnt vmcnt(8)
	s_waitcnt lgkmcnt(0)
	s_barrier
	s_waitcnt lgkmcnt(0)
	v_mfma_f32_16x16x32_bf16 v[62:65], v[114:117], v[162:165], v[62:65]
	v_mfma_f32_16x16x32_bf16 v[58:61], v[122:125], v[162:165], v[58:61]
	v_mfma_f32_16x16x32_bf16 v[46:49], v[114:117], v[184:187], v[46:49]
	v_mfma_f32_16x16x32_bf16 v[42:45], v[122:125], v[184:187], v[42:45]
	v_mfma_f32_16x16x32_bf16 v[30:33], v[114:117], v[192:195], v[30:33]
	v_mfma_f32_16x16x32_bf16 v[26:29], v[122:125], v[192:195], v[26:29]
	v_mfma_f32_16x16x32_bf16 v[14:17], v[114:117], v[204:207], v[14:17]
	v_mfma_f32_16x16x32_bf16 v[10:13], v[122:125], v[204:207], v[10:13]
	v_mfma_f32_16x16x32_bf16 v[62:65], v[118:121], v[166:169], v[62:65]
	v_mfma_f32_16x16x32_bf16 v[58:61], v[126:129], v[166:169], v[58:61]
	v_mfma_f32_16x16x32_bf16 v[46:49], v[118:121], v[188:191], v[46:49]
	v_mfma_f32_16x16x32_bf16 v[42:45], v[126:129], v[188:191], v[42:45]
	v_mfma_f32_16x16x32_bf16 v[30:33], v[118:121], v[200:203], v[30:33]
	v_mfma_f32_16x16x32_bf16 v[26:29], v[126:129], v[200:203], v[26:29]
	v_mfma_f32_16x16x32_bf16 v[14:17], v[118:121], v[236:239], v[14:17]
	v_mfma_f32_16x16x32_bf16 v[10:13], v[126:129], v[236:239], v[10:13]
	v_mfma_f32_16x16x32_bf16 v[54:57], v[146:149], v[162:165], v[54:57]
	v_mfma_f32_16x16x32_bf16 v[50:53], v[154:157], v[162:165], v[50:53]
	v_mfma_f32_16x16x32_bf16 v[38:41], v[146:149], v[184:187], v[38:41]
	v_mfma_f32_16x16x32_bf16 v[34:37], v[154:157], v[184:187], v[34:37]
	v_mfma_f32_16x16x32_bf16 v[22:25], v[146:149], v[192:195], v[22:25]
	v_mfma_f32_16x16x32_bf16 v[18:21], v[154:157], v[192:195], v[18:21]
	v_mfma_f32_16x16x32_bf16 v[6:9], v[146:149], v[204:207], v[6:9]
	v_mfma_f32_16x16x32_bf16 v[2:5], v[154:157], v[204:207], v[2:5]
	v_mfma_f32_16x16x32_bf16 v[54:57], v[150:153], v[166:169], v[54:57]
	v_mfma_f32_16x16x32_bf16 v[50:53], v[158:161], v[166:169], v[50:53]
	v_mfma_f32_16x16x32_bf16 v[38:41], v[150:153], v[188:191], v[38:41]
	v_mfma_f32_16x16x32_bf16 v[34:37], v[158:161], v[188:191], v[34:37]
	v_mfma_f32_16x16x32_bf16 v[22:25], v[150:153], v[200:203], v[22:25]
	v_mfma_f32_16x16x32_bf16 v[18:21], v[158:161], v[200:203], v[18:21]
	v_mfma_f32_16x16x32_bf16 v[6:9], v[150:153], v[236:239], v[6:9]
	v_mfma_f32_16x16x32_bf16 v[2:5], v[158:161], v[236:239], v[2:5]
	s_barrier
	s_add_u32 s10, s10, 0x100
	s_addc_u32 s11, s11, 0
	s_add_u32 s14, s14, 0x100
	s_addc_u32 s15, s15, 0
	s_cmp_ge_u32 vcc_lo, s77
	s_mov_b32 s12, vcc_lo
	s_cbranch_scc0 .LBB0_194
	s_setprio 0
	s_and_b64 vcc, exec, s[54:55]
	s_cbranch_vccz .LBB0_197
	s_barrier

.LBB0_218:
	s_add_u32 s18, s18, 0x80
	s_addc_u32 s19, s19, 0
	s_add_u32 s11, s48, 0x100
	v_mov_b32_e32 v2, 0
	s_addc_u32 s15, s49, 0
	s_mov_b32 s48, 0
	v_mov_b32_e32 v3, v2
	v_pk_mov_b32 v[4:5], v[2:3], v[2:3] op_sel:[0,1]
	v_pk_mov_b32 v[6:7], v[2:3], v[2:3] op_sel:[0,1]
	v_pk_mov_b32 v[8:9], v[2:3], v[2:3] op_sel:[0,1]
	v_pk_mov_b32 v[10:11], v[2:3], v[2:3] op_sel:[0,1]
	v_pk_mov_b32 v[12:13], v[2:3], v[2:3] op_sel:[0,1]
	v_pk_mov_b32 v[14:15], v[2:3], v[2:3] op_sel:[0,1]
	v_pk_mov_b32 v[16:17], v[2:3], v[2:3] op_sel:[0,1]
	v_pk_mov_b32 v[22:23], v[2:3], v[2:3] op_sel:[0,1]
	v_pk_mov_b32 v[24:25], v[2:3], v[2:3] op_sel:[0,1]
	v_pk_mov_b32 v[30:31], v[2:3], v[2:3] op_sel:[0,1]
	v_pk_mov_b32 v[32:33], v[2:3], v[2:3] op_sel:[0,1]
	v_pk_mov_b32 v[38:39], v[2:3], v[2:3] op_sel:[0,1]
	v_pk_mov_b32 v[40:41], v[2:3], v[2:3] op_sel:[0,1]
	v_pk_mov_b32 v[46:47], v[2:3], v[2:3] op_sel:[0,1]
	v_pk_mov_b32 v[48:49], v[2:3], v[2:3] op_sel:[0,1]
	v_pk_mov_b32 v[18:19], v[2:3], v[2:3] op_sel:[0,1]
	v_pk_mov_b32 v[20:21], v[2:3], v[2:3] op_sel:[0,1]
	v_pk_mov_b32 v[26:27], v[2:3], v[2:3] op_sel:[0,1]
	v_pk_mov_b32 v[28:29], v[2:3], v[2:3] op_sel:[0,1]
	v_pk_mov_b32 v[34:35], v[2:3], v[2:3] op_sel:[0,1]
	v_pk_mov_b32 v[36:37], v[2:3], v[2:3] op_sel:[0,1]
	v_pk_mov_b32 v[42:43], v[2:3], v[2:3] op_sel:[0,1]
	v_pk_mov_b32 v[44:45], v[2:3], v[2:3] op_sel:[0,1]
	v_pk_mov_b32 v[50:51], v[2:3], v[2:3] op_sel:[0,1]
	v_pk_mov_b32 v[52:53], v[2:3], v[2:3] op_sel:[0,1]
	v_pk_mov_b32 v[54:55], v[2:3], v[2:3] op_sel:[0,1]
	v_pk_mov_b32 v[56:57], v[2:3], v[2:3] op_sel:[0,1]
	v_pk_mov_b32 v[58:59], v[2:3], v[2:3] op_sel:[0,1]
	v_pk_mov_b32 v[60:61], v[2:3], v[2:3] op_sel:[0,1]
	v_pk_mov_b32 v[62:63], v[2:3], v[2:3] op_sel:[0,1]
	v_pk_mov_b32 v[64:65], v[2:3], v[2:3] op_sel:[0,1]
	v_pk_mov_b32 v[66:67], v[2:3], v[2:3] op_sel:[0,1]
	v_pk_mov_b32 v[68:69], v[2:3], v[2:3] op_sel:[0,1]
	v_pk_mov_b32 v[70:71], v[2:3], v[2:3] op_sel:[0,1]
	v_pk_mov_b32 v[72:73], v[2:3], v[2:3] op_sel:[0,1]
	v_pk_mov_b32 v[74:75], v[2:3], v[2:3] op_sel:[0,1]
	v_pk_mov_b32 v[76:77], v[2:3], v[2:3] op_sel:[0,1]
	v_pk_mov_b32 v[78:79], v[2:3], v[2:3] op_sel:[0,1]
	v_pk_mov_b32 v[80:81], v[2:3], v[2:3] op_sel:[0,1]
	v_pk_mov_b32 v[86:87], v[2:3], v[2:3] op_sel:[0,1]
	v_pk_mov_b32 v[88:89], v[2:3], v[2:3] op_sel:[0,1]
	v_pk_mov_b32 v[94:95], v[2:3], v[2:3] op_sel:[0,1]
	v_pk_mov_b32 v[96:97], v[2:3], v[2:3] op_sel:[0,1]
	v_pk_mov_b32 v[102:103], v[2:3], v[2:3] op_sel:[0,1]
	v_pk_mov_b32 v[104:105], v[2:3], v[2:3] op_sel:[0,1]
	v_pk_mov_b32 v[110:111], v[2:3], v[2:3] op_sel:[0,1]
	v_pk_mov_b32 v[112:113], v[2:3], v[2:3] op_sel:[0,1]
	v_pk_mov_b32 v[82:83], v[2:3], v[2:3] op_sel:[0,1]
	v_pk_mov_b32 v[84:85], v[2:3], v[2:3] op_sel:[0,1]
	v_pk_mov_b32 v[90:91], v[2:3], v[2:3] op_sel:[0,1]
	v_pk_mov_b32 v[92:93], v[2:3], v[2:3] op_sel:[0,1]
	v_pk_mov_b32 v[98:99], v[2:3], v[2:3] op_sel:[0,1]
	v_pk_mov_b32 v[100:101], v[2:3], v[2:3] op_sel:[0,1]
	v_pk_mov_b32 v[106:107], v[2:3], v[2:3] op_sel:[0,1]
	v_pk_mov_b32 v[108:109], v[2:3], v[2:3] op_sel:[0,1]
	v_pk_mov_b32 v[114:115], v[2:3], v[2:3] op_sel:[0,1]
	v_pk_mov_b32 v[116:117], v[2:3], v[2:3] op_sel:[0,1]
	v_pk_mov_b32 v[118:119], v[2:3], v[2:3] op_sel:[0,1]
	v_pk_mov_b32 v[120:121], v[2:3], v[2:3] op_sel:[0,1]
	v_pk_mov_b32 v[122:123], v[2:3], v[2:3] op_sel:[0,1]
	v_pk_mov_b32 v[124:125], v[2:3], v[2:3] op_sel:[0,1]
	v_pk_mov_b32 v[126:127], v[2:3], v[2:3] op_sel:[0,1]
	v_pk_mov_b32 v[128:129], v[2:3], v[2:3] op_sel:[0,1]
	v_readfirstlane_b32 s98, v208
	s_bitcmp1_b32 s98, 8
	s_cbranch_scc0 .Lsp_219
	s_setprio 1
.Lsp_219:
.LBB0_219:
	s_add_i32 vcc_lo, s48, 2
	s_add_u32 s36, s18, 0x80
	s_addc_u32 s37, s19, 0
	s_add_i32 vcc_hi, 0, 0x10000
	s_cmp_eq_u32 s89, s48
	s_cselect_b32 s49, s17, s37
	s_cselect_b32 s48, s16, s36
	s_cselect_b32 s37, s45, s15
	s_cselect_b32 s36, s44, s11
	s_add_i32 s28, 0, 0x14000
	v_add_u32_e32 v156, vcc_hi, v141
	v_add_u32_e32 v168, s28, v141
	ds_read_b128 v[144:147], v156
	ds_read_b128 v[148:151], v156 offset:1024
	ds_read_b128 v[152:155], v156 offset:2048
	ds_read_b128 v[156:159], v156 offset:3072
	ds_read_b128 v[160:163], v168
	ds_read_b128 v[164:167], v168 offset:1024
	ds_read_b128 v[174:177], v168 offset:2048
	ds_read_b128 v[178:181], v168 offset:3072
	v_lshl_add_u64 v[168:169], s[18:19], 0, v[136:137]
	s_add_i32 m0, s54, 0xc000
	ds_read_b128 v[182:185], v143
	ds_read_b128 v[186:189], v143 offset:1024
	ds_read_b128 v[190:193], v143 offset:2048
	ds_read_b128 v[194:197], v143 offset:3072
	ds_read_b128 v[198:201], v143 offset:4096
	ds_read_b128 v[202:205], v143 offset:5120
	ds_read_b128 v[236:239], v143 offset:6144
	ds_read_b128 v[240:243], v143 offset:7168
	global_load_lds_dwordx4 v[168:169], off
	v_lshl_add_u64 v[168:169], s[18:19], 0, v[138:139]
	s_add_i32 m0, s54, 0xe000
	s_nop 0
	global_load_lds_dwordx4 v[168:169], off
	s_waitcnt vmcnt(8)
	s_waitcnt lgkmcnt(0)
	s_barrier
	s_waitcnt lgkmcnt(0)
	v_mfma_f32_16x16x32_bf16 v[126:129], v[144:147], v[182:185], v[126:129]
	v_mfma_f32_16x16x32_bf16 v[122:125], v[152:155], v[182:185], v[122:125]
	v_mfma_f32_16x16x32_bf16 v[118:121], v[144:147], v[190:193], v[118:121]
	v_mfma_f32_16x16x32_bf16 v[114:117], v[152:155], v[190:193], v[114:117]
	v_mfma_f32_16x16x32_bf16 v[106:109], v[144:147], v[198:201], v[106:109]
	v_mfma_f32_16x16x32_bf16 v[98:101], v[152:155], v[198:201], v[98:101]
	v_mfma_f32_16x16x32_bf16 v[90:93], v[144:147], v[236:239], v[90:93]
	v_mfma_f32_16x16x32_bf16 v[82:85], v[152:155], v[236:239], v[82:85]
	v_mfma_f32_16x16x32_bf16 v[126:129], v[148:151], v[186:189], v[126:129]
	v_mfma_f32_16x16x32_bf16 v[122:125], v[156:159], v[186:189], v[122:125]
	v_mfma_f32_16x16x32_bf16 v[118:121], v[148:151], v[194:197], v[118:121]
	v_mfma_f32_16x16x32_bf16 v[114:117], v[156:159], v[194:197], v[114:117]
	v_mfma_f32_16x16x32_bf16 v[106:109], v[148:151], v[202:205], v[106:109]
	v_mfma_f32_16x16x32_bf16 v[98:101], v[156:159], v[202:205], v[98:101]
	v_mfma_f32_16x16x32_bf16 v[90:93], v[148:151], v[240:243], v[90:93]
	v_mfma_f32_16x16x32_bf16 v[82:85], v[156:159], v[240:243], v[82:85]
	v_mfma_f32_16x16x32_bf16 v[110:113], v[160:163], v[182:185], v[110:113]
	v_mfma_f32_16x16x32_bf16 v[102:105], v[174:177], v[182:185], v[102:105]
	v_mfma_f32_16x16x32_bf16 v[94:97], v[160:163], v[190:193], v[94:97]
	v_mfma_f32_16x16x32_bf16 v[86:89], v[174:177], v[190:193], v[86:89]
	v_mfma_f32_16x16x32_bf16 v[78:81], v[160:163], v[198:201], v[78:81]
	v_mfma_f32_16x16x32_bf16 v[74:77], v[174:177], v[198:201], v[74:77]
	v_mfma_f32_16x16x32_bf16 v[70:73], v[160:163], v[236:239], v[70:73]
	v_mfma_f32_16x16x32_bf16 v[66:69], v[174:177], v[236:239], v[66:69]
	v_mfma_f32_16x16x32_bf16 v[110:113], v[164:167], v[186:189], v[110:113]
	v_mfma_f32_16x16x32_bf16 v[102:105], v[178:181], v[186:189], v[102:105]
	v_mfma_f32_16x16x32_bf16 v[94:97], v[164:167], v[194:197], v[94:97]
	v_mfma_f32_16x16x32_bf16 v[86:89], v[178:181], v[194:197], v[86:89]
	v_mfma_f32_16x16x32_bf16 v[78:81], v[164:167], v[202:205], v[78:81]
	v_mfma_f32_16x16x32_bf16 v[74:77], v[178:181], v[202:205], v[74:77]
	v_mfma_f32_16x16x32_bf16 v[70:73], v[164:167], v[240:243], v[70:73]
	v_mfma_f32_16x16x32_bf16 v[66:69], v[178:181], v[240:243], v[66:69]
	s_barrier
	s_add_i32 s29, vcc_hi, s41
	v_lshl_add_u64 v[168:169], s[36:37], 0, v[0:1]
	s_mov_b32 m0, s29
	ds_read_b128 v[182:185], v143 offset:16384
	ds_read_b128 v[186:189], v143 offset:17408
	ds_read_b128 v[190:193], v143 offset:18432
	ds_read_b128 v[194:197], v143 offset:19456
	ds_read_b128 v[198:201], v143 offset:20480
	ds_read_b128 v[202:205], v143 offset:21504
	ds_read_b128 v[236:239], v143 offset:22528
	ds_read_b128 v[240:243], v143 offset:23552
	global_load_lds_dwordx4 v[168:169], off
	s_add_i32 m0, s29, 0x2000
	v_lshl_add_u64 v[206:207], s[36:37], 0, v[130:131]
	s_add_u32 s36, s36, s20
	s_addc_u32 s37, s37, 0
	s_add_i32 s28, s28, s41
	global_load_lds_dwordx4 v[206:207], off
	v_lshl_add_u64 v[228:229], s[36:37], 0, v[0:1]
	s_mov_b32 m0, s28
	v_lshl_add_u64 v[244:245], s[36:37], 0, v[130:131]
	global_load_lds_dwordx4 v[228:229], off
	s_add_i32 m0, s28, 0x2000
	v_lshl_add_u64 v[246:247], s[48:49], 0, v[134:135]
	global_load_lds_dwordx4 v[244:245], off
	s_mov_b32 m0, s54
	v_lshl_add_u64 v[248:249], s[48:49], 0, v[132:133]
	global_load_lds_dwordx4 v[246:247], off
	s_mov_b32 m0, s55
	s_nop 0
	global_load_lds_dwordx4 v[248:249], off
	s_waitcnt vmcnt(8)
	s_waitcnt lgkmcnt(0)
	s_barrier
	s_waitcnt lgkmcnt(0)
	v_mfma_f32_16x16x32_bf16 v[62:65], v[144:147], v[182:185], v[62:65]
	v_mfma_f32_16x16x32_bf16 v[58:61], v[152:155], v[182:185], v[58:61]
	v_mfma_f32_16x16x32_bf16 v[54:57], v[144:147], v[190:193], v[54:57]
	v_mfma_f32_16x16x32_bf16 v[50:53], v[152:155], v[190:193], v[50:53]
	v_mfma_f32_16x16x32_bf16 v[42:45], v[144:147], v[198:201], v[42:45]
	v_mfma_f32_16x16x32_bf16 v[34:37], v[152:155], v[198:201], v[34:37]
	v_mfma_f32_16x16x32_bf16 v[26:29], v[144:147], v[236:239], v[26:29]
	v_mfma_f32_16x16x32_bf16 v[18:21], v[152:155], v[236:239], v[18:21]
	v_mfma_f32_16x16x32_bf16 v[62:65], v[148:151], v[186:189], v[62:65]
	v_mfma_f32_16x16x32_bf16 v[58:61], v[156:159], v[186:189], v[58:61]
	v_mfma_f32_16x16x32_bf16 v[54:57], v[148:151], v[194:197], v[54:57]
	v_mfma_f32_16x16x32_bf16 v[50:53], v[156:159], v[194:197], v[50:53]
	v_mfma_f32_16x16x32_bf16 v[42:45], v[148:151], v[202:205], v[42:45]
	v_mfma_f32_16x16x32_bf16 v[34:37], v[156:159], v[202:205], v[34:37]
	v_mfma_f32_16x16x32_bf16 v[26:29], v[148:151], v[240:243], v[26:29]
	v_mfma_f32_16x16x32_bf16 v[18:21], v[156:159], v[240:243], v[18:21]
	v_mfma_f32_16x16x32_bf16 v[46:49], v[160:163], v[182:185], v[46:49]
	v_mfma_f32_16x16x32_bf16 v[38:41], v[174:177], v[182:185], v[38:41]
	v_mfma_f32_16x16x32_bf16 v[30:33], v[160:163], v[190:193], v[30:33]
	v_mfma_f32_16x16x32_bf16 v[22:25], v[174:177], v[190:193], v[22:25]
	v_mfma_f32_16x16x32_bf16 v[14:17], v[160:163], v[198:201], v[14:17]
	v_mfma_f32_16x16x32_bf16 v[10:13], v[174:177], v[198:201], v[10:13]
	v_mfma_f32_16x16x32_bf16 v[6:9], v[160:163], v[236:239], v[6:9]
	v_mfma_f32_16x16x32_bf16 v[2:5], v[174:177], v[236:239], v[2:5]
	v_mfma_f32_16x16x32_bf16 v[46:49], v[164:167], v[186:189], v[46:49]
	v_mfma_f32_16x16x32_bf16 v[38:41], v[178:181], v[186:189], v[38:41]
	v_mfma_f32_16x16x32_bf16 v[30:33], v[164:167], v[194:197], v[30:33]
	v_mfma_f32_16x16x32_bf16 v[22:25], v[178:181], v[194:197], v[22:25]
	v_mfma_f32_16x16x32_bf16 v[14:17], v[164:167], v[202:205], v[14:17]
	v_mfma_f32_16x16x32_bf16 v[10:13], v[178:181], v[202:205], v[10:13]
	v_mfma_f32_16x16x32_bf16 v[6:9], v[164:167], v[240:243], v[6:9]
	v_mfma_f32_16x16x32_bf16 v[2:5], v[178:181], v[240:243], v[2:5]
	s_barrier
	s_add_i32 s28, 0, 0x18000
	s_add_i32 s29, 0, 0x1c000
	v_add_u32_e32 v156, s28, v141
	v_add_u32_e32 v178, s29, v141
	ds_read_b128 v[144:147], v156
	ds_read_b128 v[148:151], v156 offset:1024
	ds_read_b128 v[152:155], v156 offset:2048
	ds_read_b128 v[156:159], v156 offset:3072
	ds_read_b128 v[160:163], v178
	ds_read_b128 v[164:167], v178 offset:1024
	ds_read_b128 v[174:177], v178 offset:2048
	ds_read_b128 v[178:181], v178 offset:3072
	s_add_u32 s36, s48, s20
	s_addc_u32 s37, s49, 0
	s_mov_b32 m0, s70
	v_lshl_add_u64 v[250:251], s[36:37], 0, v[134:135]
	ds_read_b128 v[182:185], v143 offset:32768
	ds_read_b128 v[186:189], v143 offset:33792
	ds_read_b128 v[190:193], v143 offset:34816
	ds_read_b128 v[194:197], v143 offset:35840
	ds_read_b128 v[198:201], v143 offset:36864
	ds_read_b128 v[202:205], v143 offset:37888
	ds_read_b128 v[236:239], v143 offset:38912
	ds_read_b128 v[240:243], v143 offset:39936
	global_load_lds_dwordx4 v[250:251], off
	v_lshl_add_u64 v[250:251], s[36:37], 0, v[132:133]
	s_mov_b32 m0, s71
	s_nop 0
	global_load_lds_dwordx4 v[250:251], off
	s_waitcnt vmcnt(8)
	s_waitcnt lgkmcnt(0)
	s_barrier
	s_waitcnt lgkmcnt(0)
	v_mfma_f32_16x16x32_bf16 v[126:129], v[144:147], v[182:185], v[126:129]
	v_mfma_f32_16x16x32_bf16 v[122:125], v[152:155], v[182:185], v[122:125]
	v_mfma_f32_16x16x32_bf16 v[118:121], v[144:147], v[190:193], v[118:121]
	v_mfma_f32_16x16x32_bf16 v[114:117], v[152:155], v[190:193], v[114:117]
	v_mfma_f32_16x16x32_bf16 v[106:109], v[144:147], v[198:201], v[106:109]
	v_mfma_f32_16x16x32_bf16 v[98:101], v[152:155], v[198:201], v[98:101]
	v_mfma_f32_16x16x32_bf16 v[90:93], v[144:147], v[236:239], v[90:93]
	v_mfma_f32_16x16x32_bf16 v[82:85], v[152:155], v[236:239], v[82:85]
	v_mfma_f32_16x16x32_bf16 v[126:129], v[148:151], v[186:189], v[126:129]
	v_mfma_f32_16x16x32_bf16 v[122:125], v[156:159], v[186:189], v[122:125]
	v_mfma_f32_16x16x32_bf16 v[118:121], v[148:151], v[194:197], v[118:121]
	v_mfma_f32_16x16x32_bf16 v[114:117], v[156:159], v[194:197], v[114:117]
	v_mfma_f32_16x16x32_bf16 v[106:109], v[148:151], v[202:205], v[106:109]
	v_mfma_f32_16x16x32_bf16 v[98:101], v[156:159], v[202:205], v[98:101]
	v_mfma_f32_16x16x32_bf16 v[90:93], v[148:151], v[240:243], v[90:93]
	v_mfma_f32_16x16x32_bf16 v[82:85], v[156:159], v[240:243], v[82:85]
	v_mfma_f32_16x16x32_bf16 v[110:113], v[160:163], v[182:185], v[110:113]
	v_mfma_f32_16x16x32_bf16 v[102:105], v[174:177], v[182:185], v[102:105]
	v_mfma_f32_16x16x32_bf16 v[94:97], v[160:163], v[190:193], v[94:97]
	v_mfma_f32_16x16x32_bf16 v[86:89], v[174:177], v[190:193], v[86:89]
	v_mfma_f32_16x16x32_bf16 v[78:81], v[160:163], v[198:201], v[78:81]
	v_mfma_f32_16x16x32_bf16 v[74:77], v[174:177], v[198:201], v[74:77]
	v_mfma_f32_16x16x32_bf16 v[70:73], v[160:163], v[236:239], v[70:73]
	v_mfma_f32_16x16x32_bf16 v[66:69], v[174:177], v[236:239], v[66:69]
	v_mfma_f32_16x16x32_bf16 v[110:113], v[164:167], v[186:189], v[110:113]
	v_mfma_f32_16x16x32_bf16 v[102:105], v[178:181], v[186:189], v[102:105]
	v_mfma_f32_16x16x32_bf16 v[94:97], v[164:167], v[194:197], v[94:97]
	v_mfma_f32_16x16x32_bf16 v[86:89], v[178:181], v[194:197], v[86:89]
	v_mfma_f32_16x16x32_bf16 v[78:81], v[164:167], v[202:205], v[78:81]
	v_mfma_f32_16x16x32_bf16 v[74:77], v[178:181], v[202:205], v[74:77]
	v_mfma_f32_16x16x32_bf16 v[70:73], v[164:167], v[240:243], v[70:73]
	v_mfma_f32_16x16x32_bf16 v[66:69], v[178:181], v[240:243], v[66:69]
	s_barrier
	s_add_i32 s28, s28, s41
	v_lshl_add_u64 v[168:169], v[168:169], 0, s[4:5]
	s_mov_b32 m0, s28
	ds_read_b128 v[182:185], v143 offset:49152
	ds_read_b128 v[186:189], v143 offset:50176
	ds_read_b128 v[190:193], v143 offset:51200
	ds_read_b128 v[194:197], v143 offset:52224
	ds_read_b128 v[198:201], v143 offset:53248
	ds_read_b128 v[202:205], v143 offset:54272
	ds_read_b128 v[236:239], v143 offset:55296
	ds_read_b128 v[240:243], v143 offset:56320
	global_load_lds_dwordx4 v[168:169], off
	v_lshl_add_u64 v[168:169], v[206:207], 0, s[4:5]
	s_add_i32 m0, s28, 0x2000
	s_add_i32 s28, s29, s41
	global_load_lds_dwordx4 v[168:169], off
	v_lshl_add_u64 v[168:169], v[228:229], 0, s[4:5]
	s_mov_b32 m0, s28
	s_nop 0
	global_load_lds_dwordx4 v[168:169], off
	v_lshl_add_u64 v[168:169], v[244:245], 0, s[4:5]
	s_add_i32 m0, s28, 0x2000
	s_nop 0
	global_load_lds_dwordx4 v[168:169], off
	v_lshl_add_u64 v[168:169], v[246:247], 0, s[4:5]
	s_mov_b32 m0, s83
	s_nop 0
	global_load_lds_dwordx4 v[168:169], off
	v_lshl_add_u64 v[168:169], v[248:249], 0, s[4:5]
	s_mov_b32 m0, s85
	s_nop 0
	global_load_lds_dwordx4 v[168:169], off
	s_waitcnt vmcnt(8)
	s_waitcnt lgkmcnt(0)
	s_barrier
	s_waitcnt lgkmcnt(0)
	v_mfma_f32_16x16x32_bf16 v[62:65], v[144:147], v[182:185], v[62:65]
	v_mfma_f32_16x16x32_bf16 v[58:61], v[152:155], v[182:185], v[58:61]
	v_mfma_f32_16x16x32_bf16 v[54:57], v[144:147], v[190:193], v[54:57]
	v_mfma_f32_16x16x32_bf16 v[50:53], v[152:155], v[190:193], v[50:53]
	v_mfma_f32_16x16x32_bf16 v[42:45], v[144:147], v[198:201], v[42:45]
	v_mfma_f32_16x16x32_bf16 v[34:37], v[152:155], v[198:201], v[34:37]
	v_mfma_f32_16x16x32_bf16 v[26:29], v[144:147], v[236:239], v[26:29]
	v_mfma_f32_16x16x32_bf16 v[18:21], v[152:155], v[236:239], v[18:21]
	v_mfma_f32_16x16x32_bf16 v[62:65], v[148:151], v[186:189], v[62:65]
	v_mfma_f32_16x16x32_bf16 v[58:61], v[156:159], v[186:189], v[58:61]
	v_mfma_f32_16x16x32_bf16 v[54:57], v[148:151], v[194:197], v[54:57]
	v_mfma_f32_16x16x32_bf16 v[50:53], v[156:159], v[194:197], v[50:53]
	v_mfma_f32_16x16x32_bf16 v[42:45], v[148:151], v[202:205], v[42:45]
	v_mfma_f32_16x16x32_bf16 v[34:37], v[156:159], v[202:205], v[34:37]
	v_mfma_f32_16x16x32_bf16 v[26:29], v[148:151], v[240:243], v[26:29]
	v_mfma_f32_16x16x32_bf16 v[18:21], v[156:159], v[240:243], v[18:21]
	v_mfma_f32_16x16x32_bf16 v[46:49], v[160:163], v[182:185], v[46:49]
	v_mfma_f32_16x16x32_bf16 v[38:41], v[174:177], v[182:185], v[38:41]
	v_mfma_f32_16x16x32_bf16 v[30:33], v[160:163], v[190:193], v[30:33]
	v_mfma_f32_16x16x32_bf16 v[22:25], v[174:177], v[190:193], v[22:25]
	v_mfma_f32_16x16x32_bf16 v[14:17], v[160:163], v[198:201], v[14:17]
	v_mfma_f32_16x16x32_bf16 v[10:13], v[174:177], v[198:201], v[10:13]
	v_mfma_f32_16x16x32_bf16 v[6:9], v[160:163], v[236:239], v[6:9]
	v_mfma_f32_16x16x32_bf16 v[2:5], v[174:177], v[236:239], v[2:5]
	v_mfma_f32_16x16x32_bf16 v[46:49], v[164:167], v[186:189], v[46:49]
	v_mfma_f32_16x16x32_bf16 v[38:41], v[178:181], v[186:189], v[38:41]
	v_mfma_f32_16x16x32_bf16 v[30:33], v[164:167], v[194:197], v[30:33]
	v_mfma_f32_16x16x32_bf16 v[22:25], v[178:181], v[194:197], v[22:25]
	v_mfma_f32_16x16x32_bf16 v[14:17], v[164:167], v[202:205], v[14:17]
	v_mfma_f32_16x16x32_bf16 v[10:13], v[178:181], v[202:205], v[10:13]
	v_mfma_f32_16x16x32_bf16 v[6:9], v[164:167], v[240:243], v[6:9]
	v_mfma_f32_16x16x32_bf16 v[2:5], v[178:181], v[240:243], v[2:5]
	s_barrier
	s_add_u32 s18, s18, 0x100
	s_addc_u32 s19, s19, 0
	s_add_u32 s11, s11, 0x100
	s_addc_u32 s15, s15, 0
	s_cmp_ge_u32 vcc_lo, s79
	s_mov_b32 s48, vcc_lo
	s_cbranch_scc0 .LBB0_219
	s_setprio 0
	s_and_b64 vcc, exec, s[8:9]
	s_cbranch_vccz .LBB0_222
	s_barrier

.LBB0_436:
	s_ashr_i32 s9, s8, 31
	s_lshl_b64 s[14:15], s[8:9], 19
	s_cmp_eq_u32 s75, 0
	s_cselect_b32 s36, s20, s16
	s_cselect_b32 s9, s39, s17
	s_cselect_b32 s37, s16, s20
	s_cselect_b32 s46, s17, s39
	s_add_u32 s50, s36, s14
	s_addc_u32 s51, s9, s15
	s_and_b64 s[14:15], s[42:43], exec
	s_cselect_b32 s9, s51, s11
	s_cselect_b32 s45, s50, s10
	s_waitcnt lgkmcnt(0)
	s_ashr_i32 s49, s48, 31
	s_lshl_b64 s[14:15], s[48:49], 19
	s_add_u32 s52, s37, s14
	s_addc_u32 s53, s46, s15
	s_and_b64 s[14:15], s[42:43], exec
	s_cselect_b32 s46, s53, s13
	s_cselect_b32 s47, s52, s12
	s_add_u32 s10, s10, 0x40080
	s_addc_u32 s11, s11, 0
	s_add_u32 s49, s12, 0x100
	v_mov_b32_e32 v2, 0
	s_addc_u32 s77, s13, 0
	s_mov_b32 s78, -2
	v_mov_b32_e32 v3, v2
	v_pk_mov_b32 v[4:5], v[2:3], v[2:3] op_sel:[0,1]
	v_pk_mov_b32 v[6:7], v[2:3], v[2:3] op_sel:[0,1]
	v_pk_mov_b32 v[8:9], v[2:3], v[2:3] op_sel:[0,1]
	v_pk_mov_b32 v[18:19], v[2:3], v[2:3] op_sel:[0,1]
	v_pk_mov_b32 v[20:21], v[2:3], v[2:3] op_sel:[0,1]
	v_pk_mov_b32 v[22:23], v[2:3], v[2:3] op_sel:[0,1]
	v_pk_mov_b32 v[24:25], v[2:3], v[2:3] op_sel:[0,1]
	v_pk_mov_b32 v[34:35], v[2:3], v[2:3] op_sel:[0,1]
	v_pk_mov_b32 v[36:37], v[2:3], v[2:3] op_sel:[0,1]
	v_pk_mov_b32 v[38:39], v[2:3], v[2:3] op_sel:[0,1]
	v_pk_mov_b32 v[40:41], v[2:3], v[2:3] op_sel:[0,1]
	v_pk_mov_b32 v[50:51], v[2:3], v[2:3] op_sel:[0,1]
	v_pk_mov_b32 v[52:53], v[2:3], v[2:3] op_sel:[0,1]
	v_pk_mov_b32 v[54:55], v[2:3], v[2:3] op_sel:[0,1]
	v_pk_mov_b32 v[56:57], v[2:3], v[2:3] op_sel:[0,1]
	v_pk_mov_b32 v[10:11], v[2:3], v[2:3] op_sel:[0,1]
	v_pk_mov_b32 v[12:13], v[2:3], v[2:3] op_sel:[0,1]
	v_pk_mov_b32 v[14:15], v[2:3], v[2:3] op_sel:[0,1]
	v_pk_mov_b32 v[16:17], v[2:3], v[2:3] op_sel:[0,1]
	v_pk_mov_b32 v[26:27], v[2:3], v[2:3] op_sel:[0,1]
	v_pk_mov_b32 v[28:29], v[2:3], v[2:3] op_sel:[0,1]
	v_pk_mov_b32 v[30:31], v[2:3], v[2:3] op_sel:[0,1]
	v_pk_mov_b32 v[32:33], v[2:3], v[2:3] op_sel:[0,1]
	v_pk_mov_b32 v[42:43], v[2:3], v[2:3] op_sel:[0,1]
	v_pk_mov_b32 v[44:45], v[2:3], v[2:3] op_sel:[0,1]
	v_pk_mov_b32 v[46:47], v[2:3], v[2:3] op_sel:[0,1]
	v_pk_mov_b32 v[48:49], v[2:3], v[2:3] op_sel:[0,1]
	v_pk_mov_b32 v[58:59], v[2:3], v[2:3] op_sel:[0,1]
	v_pk_mov_b32 v[60:61], v[2:3], v[2:3] op_sel:[0,1]
	v_pk_mov_b32 v[62:63], v[2:3], v[2:3] op_sel:[0,1]
	v_pk_mov_b32 v[64:65], v[2:3], v[2:3] op_sel:[0,1]
	v_pk_mov_b32 v[66:67], v[2:3], v[2:3] op_sel:[0,1]
	v_pk_mov_b32 v[68:69], v[2:3], v[2:3] op_sel:[0,1]
	v_pk_mov_b32 v[70:71], v[2:3], v[2:3] op_sel:[0,1]
	v_pk_mov_b32 v[72:73], v[2:3], v[2:3] op_sel:[0,1]
	v_pk_mov_b32 v[82:83], v[2:3], v[2:3] op_sel:[0,1]
	v_pk_mov_b32 v[84:85], v[2:3], v[2:3] op_sel:[0,1]
	v_pk_mov_b32 v[86:87], v[2:3], v[2:3] op_sel:[0,1]
	v_pk_mov_b32 v[88:89], v[2:3], v[2:3] op_sel:[0,1]
	v_pk_mov_b32 v[98:99], v[2:3], v[2:3] op_sel:[0,1]
	v_pk_mov_b32 v[100:101], v[2:3], v[2:3] op_sel:[0,1]
	v_pk_mov_b32 v[102:103], v[2:3], v[2:3] op_sel:[0,1]
	v_pk_mov_b32 v[104:105], v[2:3], v[2:3] op_sel:[0,1]
	v_pk_mov_b32 v[114:115], v[2:3], v[2:3] op_sel:[0,1]
	v_pk_mov_b32 v[116:117], v[2:3], v[2:3] op_sel:[0,1]
	v_pk_mov_b32 v[118:119], v[2:3], v[2:3] op_sel:[0,1]
	v_pk_mov_b32 v[120:121], v[2:3], v[2:3] op_sel:[0,1]
	v_pk_mov_b32 v[74:75], v[2:3], v[2:3] op_sel:[0,1]
	v_pk_mov_b32 v[76:77], v[2:3], v[2:3] op_sel:[0,1]
	v_pk_mov_b32 v[78:79], v[2:3], v[2:3] op_sel:[0,1]
	v_pk_mov_b32 v[80:81], v[2:3], v[2:3] op_sel:[0,1]
	v_pk_mov_b32 v[90:91], v[2:3], v[2:3] op_sel:[0,1]
	v_pk_mov_b32 v[92:93], v[2:3], v[2:3] op_sel:[0,1]
	v_pk_mov_b32 v[94:95], v[2:3], v[2:3] op_sel:[0,1]
	v_pk_mov_b32 v[96:97], v[2:3], v[2:3] op_sel:[0,1]
	v_pk_mov_b32 v[106:107], v[2:3], v[2:3] op_sel:[0,1]
	v_pk_mov_b32 v[108:109], v[2:3], v[2:3] op_sel:[0,1]
	v_pk_mov_b32 v[110:111], v[2:3], v[2:3] op_sel:[0,1]
	v_pk_mov_b32 v[112:113], v[2:3], v[2:3] op_sel:[0,1]
	v_pk_mov_b32 v[122:123], v[2:3], v[2:3] op_sel:[0,1]
	v_pk_mov_b32 v[124:125], v[2:3], v[2:3] op_sel:[0,1]
	v_pk_mov_b32 v[126:127], v[2:3], v[2:3] op_sel:[0,1]
	v_pk_mov_b32 v[128:129], v[2:3], v[2:3] op_sel:[0,1]
	v_readfirstlane_b32 s98, v208
	s_bitcmp1_b32 s98, 8
	s_cbranch_scc0 .Lsp_437
	s_setprio 1
.Lsp_437:
.LBB0_437:
	s_add_u32 s12, s10, 0xfffc0080
	s_addc_u32 s13, s11, -1
	s_add_i32 s36, 0, 0x10000
	s_cmp_eq_u32 s78, 12
	s_cselect_b32 s15, s9, s13
	s_cselect_b32 s14, s45, s12
	s_cselect_b32 s13, s46, s77
	s_cselect_b32 s12, s47, s49
	s_add_i32 s37, 0, 0x14000
	v_add_u32_e32 v156, s36, v145
	v_add_u32_e32 v168, s37, v145
	ds_read_b128 v[140:143], v156
	ds_read_b128 v[148:151], v156 offset:1024
	ds_read_b128 v[152:155], v156 offset:2048
	ds_read_b128 v[156:159], v156 offset:3072
	ds_read_b128 v[160:163], v168
	ds_read_b128 v[164:167], v168 offset:1024
	ds_read_b128 v[174:177], v168 offset:2048
	ds_read_b128 v[178:181], v168 offset:3072
	v_lshl_add_u64 v[168:169], s[10:11], 0, v[136:137]
	s_add_i32 m0, s19, 0xc000
	ds_read_b128 v[182:185], v147
	ds_read_b128 v[186:189], v147 offset:1024
	ds_read_b128 v[190:193], v147 offset:2048
	ds_read_b128 v[194:197], v147 offset:3072
	ds_read_b128 v[198:201], v147 offset:4096
	ds_read_b128 v[202:205], v147 offset:5120
	ds_read_b128 v[236:239], v147 offset:6144
	ds_read_b128 v[240:243], v147 offset:7168
	global_load_lds_dwordx4 v[168:169], off
	v_lshl_add_u64 v[168:169], s[10:11], 0, v[138:139]
	s_add_i32 m0, s19, 0xe000
	s_nop 0
	global_load_lds_dwordx4 v[168:169], off
	s_waitcnt vmcnt(8)
	s_waitcnt lgkmcnt(0)
	s_barrier
	s_waitcnt lgkmcnt(0)
	v_mfma_f32_16x16x32_bf16 v[126:129], v[140:143], v[182:185], v[126:129]
	v_mfma_f32_16x16x32_bf16 v[122:125], v[152:155], v[182:185], v[122:125]
	v_mfma_f32_16x16x32_bf16 v[110:113], v[140:143], v[190:193], v[110:113]
	v_mfma_f32_16x16x32_bf16 v[106:109], v[152:155], v[190:193], v[106:109]
	v_mfma_f32_16x16x32_bf16 v[94:97], v[140:143], v[198:201], v[94:97]
	v_mfma_f32_16x16x32_bf16 v[90:93], v[152:155], v[198:201], v[90:93]
	v_mfma_f32_16x16x32_bf16 v[78:81], v[140:143], v[236:239], v[78:81]
	v_mfma_f32_16x16x32_bf16 v[74:77], v[152:155], v[236:239], v[74:77]
	v_mfma_f32_16x16x32_bf16 v[126:129], v[148:151], v[186:189], v[126:129]
	v_mfma_f32_16x16x32_bf16 v[122:125], v[156:159], v[186:189], v[122:125]
	v_mfma_f32_16x16x32_bf16 v[110:113], v[148:151], v[194:197], v[110:113]
	v_mfma_f32_16x16x32_bf16 v[106:109], v[156:159], v[194:197], v[106:109]
	v_mfma_f32_16x16x32_bf16 v[94:97], v[148:151], v[202:205], v[94:97]
	v_mfma_f32_16x16x32_bf16 v[90:93], v[156:159], v[202:205], v[90:93]
	v_mfma_f32_16x16x32_bf16 v[78:81], v[148:151], v[240:243], v[78:81]
	v_mfma_f32_16x16x32_bf16 v[74:77], v[156:159], v[240:243], v[74:77]
	v_mfma_f32_16x16x32_bf16 v[118:121], v[160:163], v[182:185], v[118:121]
	v_mfma_f32_16x16x32_bf16 v[114:117], v[174:177], v[182:185], v[114:117]
	v_mfma_f32_16x16x32_bf16 v[102:105], v[160:163], v[190:193], v[102:105]
	v_mfma_f32_16x16x32_bf16 v[98:101], v[174:177], v[190:193], v[98:101]
	v_mfma_f32_16x16x32_bf16 v[86:89], v[160:163], v[198:201], v[86:89]
	v_mfma_f32_16x16x32_bf16 v[82:85], v[174:177], v[198:201], v[82:85]
	v_mfma_f32_16x16x32_bf16 v[70:73], v[160:163], v[236:239], v[70:73]
	v_mfma_f32_16x16x32_bf16 v[66:69], v[174:177], v[236:239], v[66:69]
	v_mfma_f32_16x16x32_bf16 v[118:121], v[164:167], v[186:189], v[118:121]
	v_mfma_f32_16x16x32_bf16 v[114:117], v[178:181], v[186:189], v[114:117]
	v_mfma_f32_16x16x32_bf16 v[102:105], v[164:167], v[194:197], v[102:105]
	v_mfma_f32_16x16x32_bf16 v[98:101], v[178:181], v[194:197], v[98:101]
	v_mfma_f32_16x16x32_bf16 v[86:89], v[164:167], v[202:205], v[86:89]
	v_mfma_f32_16x16x32_bf16 v[82:85], v[178:181], v[202:205], v[82:85]
	v_mfma_f32_16x16x32_bf16 v[70:73], v[164:167], v[240:243], v[70:73]
	v_mfma_f32_16x16x32_bf16 v[66:69], v[178:181], v[240:243], v[66:69]
	s_barrier
	s_add_i32 s36, s36, s18
	v_lshl_add_u64 v[168:169], s[12:13], 0, v[0:1]
	s_mov_b32 m0, s36
	ds_read_b128 v[182:185], v147 offset:16384
	ds_read_b128 v[186:189], v147 offset:17408
	ds_read_b128 v[190:193], v147 offset:18432
	ds_read_b128 v[194:197], v147 offset:19456
	ds_read_b128 v[198:201], v147 offset:20480
	ds_read_b128 v[202:205], v147 offset:21504
	ds_read_b128 v[236:239], v147 offset:22528
	ds_read_b128 v[240:243], v147 offset:23552
	global_load_lds_dwordx4 v[168:169], off
	s_add_i32 m0, s36, 0x2000
	s_add_u32 s82, s12, 0x40000
	v_lshl_add_u64 v[206:207], s[12:13], 0, v[130:131]
	s_addc_u32 s83, s13, 0
	s_add_i32 s36, s37, s18
	global_load_lds_dwordx4 v[206:207], off
	v_lshl_add_u64 v[244:245], s[82:83], 0, v[0:1]
	s_mov_b32 m0, s36
	v_lshl_add_u64 v[246:247], s[14:15], 0, v[132:133]
	global_load_lds_dwordx4 v[244:245], off
	v_lshl_add_u64 v[244:245], s[82:83], 0, v[130:131]
	s_add_i32 m0, s36, 0x2000
	s_nop 0
	global_load_lds_dwordx4 v[244:245], off
	v_lshl_add_u64 v[244:245], s[14:15], 0, v[134:135]
	s_mov_b32 m0, s19
	s_nop 0
	global_load_lds_dwordx4 v[244:245], off
	s_mov_b32 m0, s34
	s_nop 0
	global_load_lds_dwordx4 v[246:247], off
	s_waitcnt vmcnt(8)
	s_waitcnt lgkmcnt(0)
	s_barrier
	s_waitcnt lgkmcnt(0)
	v_mfma_f32_16x16x32_bf16 v[62:65], v[140:143], v[182:185], v[62:65]
	v_mfma_f32_16x16x32_bf16 v[58:61], v[152:155], v[182:185], v[58:61]
	v_mfma_f32_16x16x32_bf16 v[46:49], v[140:143], v[190:193], v[46:49]
	v_mfma_f32_16x16x32_bf16 v[42:45], v[152:155], v[190:193], v[42:45]
	v_mfma_f32_16x16x32_bf16 v[30:33], v[140:143], v[198:201], v[30:33]
	v_mfma_f32_16x16x32_bf16 v[26:29], v[152:155], v[198:201], v[26:29]
	v_mfma_f32_16x16x32_bf16 v[14:17], v[140:143], v[236:239], v[14:17]
	v_mfma_f32_16x16x32_bf16 v[10:13], v[152:155], v[236:239], v[10:13]
	v_mfma_f32_16x16x32_bf16 v[62:65], v[148:151], v[186:189], v[62:65]
	v_mfma_f32_16x16x32_bf16 v[58:61], v[156:159], v[186:189], v[58:61]
	v_mfma_f32_16x16x32_bf16 v[46:49], v[148:151], v[194:197], v[46:49]
	v_mfma_f32_16x16x32_bf16 v[42:45], v[156:159], v[194:197], v[42:45]
	v_mfma_f32_16x16x32_bf16 v[30:33], v[148:151], v[202:205], v[30:33]
	v_mfma_f32_16x16x32_bf16 v[26:29], v[156:159], v[202:205], v[26:29]
	v_mfma_f32_16x16x32_bf16 v[14:17], v[148:151], v[240:243], v[14:17]
	v_mfma_f32_16x16x32_bf16 v[10:13], v[156:159], v[240:243], v[10:13]
	v_mfma_f32_16x16x32_bf16 v[54:57], v[160:163], v[182:185], v[54:57]
	v_mfma_f32_16x16x32_bf16 v[50:53], v[174:177], v[182:185], v[50:53]
	v_mfma_f32_16x16x32_bf16 v[38:41], v[160:163], v[190:193], v[38:41]
	v_mfma_f32_16x16x32_bf16 v[34:37], v[174:177], v[190:193], v[34:37]
	v_mfma_f32_16x16x32_bf16 v[22:25], v[160:163], v[198:201], v[22:25]
	v_mfma_f32_16x16x32_bf16 v[18:21], v[174:177], v[198:201], v[18:21]
	v_mfma_f32_16x16x32_bf16 v[6:9], v[160:163], v[236:239], v[6:9]
	v_mfma_f32_16x16x32_bf16 v[2:5], v[174:177], v[236:239], v[2:5]
	v_mfma_f32_16x16x32_bf16 v[54:57], v[164:167], v[186:189], v[54:57]
	v_mfma_f32_16x16x32_bf16 v[50:53], v[178:181], v[186:189], v[50:53]
	v_mfma_f32_16x16x32_bf16 v[38:41], v[164:167], v[194:197], v[38:41]
	v_mfma_f32_16x16x32_bf16 v[34:37], v[178:181], v[194:197], v[34:37]
	v_mfma_f32_16x16x32_bf16 v[22:25], v[164:167], v[202:205], v[22:25]
	v_mfma_f32_16x16x32_bf16 v[18:21], v[178:181], v[202:205], v[18:21]
	v_mfma_f32_16x16x32_bf16 v[6:9], v[164:167], v[240:243], v[6:9]
	v_mfma_f32_16x16x32_bf16 v[2:5], v[178:181], v[240:243], v[2:5]
	s_barrier
	s_add_i32 s36, 0, 0x18000
	s_add_i32 s37, 0, 0x1c000
	v_add_u32_e32 v156, s36, v145
	v_add_u32_e32 v178, s37, v145
	ds_read_b128 v[140:143], v156
	ds_read_b128 v[148:151], v156 offset:1024
	ds_read_b128 v[152:155], v156 offset:2048
	ds_read_b128 v[156:159], v156 offset:3072
	ds_read_b128 v[160:163], v178
	ds_read_b128 v[164:167], v178 offset:1024
	ds_read_b128 v[174:177], v178 offset:2048
	ds_read_b128 v[178:181], v178 offset:3072
	s_add_u32 s14, s14, 0x40000
	s_addc_u32 s15, s15, 0
	s_mov_b32 m0, s54
	v_lshl_add_u64 v[248:249], s[14:15], 0, v[134:135]
	ds_read_b128 v[182:185], v147 offset:32768
	ds_read_b128 v[186:189], v147 offset:33792
	ds_read_b128 v[190:193], v147 offset:34816
	ds_read_b128 v[194:197], v147 offset:35840
	ds_read_b128 v[198:201], v147 offset:36864
	ds_read_b128 v[202:205], v147 offset:37888
	ds_read_b128 v[236:239], v147 offset:38912
	ds_read_b128 v[240:243], v147 offset:39936
	global_load_lds_dwordx4 v[248:249], off
	v_lshl_add_u64 v[248:249], s[14:15], 0, v[132:133]
	s_mov_b32 m0, s55
	s_nop 0
	global_load_lds_dwordx4 v[248:249], off
	s_waitcnt vmcnt(8)
	s_waitcnt lgkmcnt(0)
	s_barrier
	s_waitcnt lgkmcnt(0)
	v_mfma_f32_16x16x32_bf16 v[126:129], v[140:143], v[182:185], v[126:129]
	v_mfma_f32_16x16x32_bf16 v[122:125], v[152:155], v[182:185], v[122:125]
	v_mfma_f32_16x16x32_bf16 v[110:113], v[140:143], v[190:193], v[110:113]
	v_mfma_f32_16x16x32_bf16 v[106:109], v[152:155], v[190:193], v[106:109]
	v_mfma_f32_16x16x32_bf16 v[94:97], v[140:143], v[198:201], v[94:97]
	v_mfma_f32_16x16x32_bf16 v[90:93], v[152:155], v[198:201], v[90:93]
	v_mfma_f32_16x16x32_bf16 v[78:81], v[140:143], v[236:239], v[78:81]
	v_mfma_f32_16x16x32_bf16 v[74:77], v[152:155], v[236:239], v[74:77]
	v_mfma_f32_16x16x32_bf16 v[126:129], v[148:151], v[186:189], v[126:129]
	v_mfma_f32_16x16x32_bf16 v[122:125], v[156:159], v[186:189], v[122:125]
	v_mfma_f32_16x16x32_bf16 v[110:113], v[148:151], v[194:197], v[110:113]
	v_mfma_f32_16x16x32_bf16 v[106:109], v[156:159], v[194:197], v[106:109]
	v_mfma_f32_16x16x32_bf16 v[94:97], v[148:151], v[202:205], v[94:97]
	v_mfma_f32_16x16x32_bf16 v[90:93], v[156:159], v[202:205], v[90:93]
	v_mfma_f32_16x16x32_bf16 v[78:81], v[148:151], v[240:243], v[78:81]
	v_mfma_f32_16x16x32_bf16 v[74:77], v[156:159], v[240:243], v[74:77]
	v_mfma_f32_16x16x32_bf16 v[118:121], v[160:163], v[182:185], v[118:121]
	v_mfma_f32_16x16x32_bf16 v[114:117], v[174:177], v[182:185], v[114:117]
	v_mfma_f32_16x16x32_bf16 v[102:105], v[160:163], v[190:193], v[102:105]
	v_mfma_f32_16x16x32_bf16 v[98:101], v[174:177], v[190:193], v[98:101]
	v_mfma_f32_16x16x32_bf16 v[86:89], v[160:163], v[198:201], v[86:89]
	v_mfma_f32_16x16x32_bf16 v[82:85], v[174:177], v[198:201], v[82:85]
	v_mfma_f32_16x16x32_bf16 v[70:73], v[160:163], v[236:239], v[70:73]
	v_mfma_f32_16x16x32_bf16 v[66:69], v[174:177], v[236:239], v[66:69]
	v_mfma_f32_16x16x32_bf16 v[118:121], v[164:167], v[186:189], v[118:121]
	v_mfma_f32_16x16x32_bf16 v[114:117], v[178:181], v[186:189], v[114:117]
	v_mfma_f32_16x16x32_bf16 v[102:105], v[164:167], v[194:197], v[102:105]
	v_mfma_f32_16x16x32_bf16 v[98:101], v[178:181], v[194:197], v[98:101]
	v_mfma_f32_16x16x32_bf16 v[86:89], v[164:167], v[202:205], v[86:89]
	v_mfma_f32_16x16x32_bf16 v[82:85], v[178:181], v[202:205], v[82:85]
	v_mfma_f32_16x16x32_bf16 v[70:73], v[164:167], v[240:243], v[70:73]
	v_mfma_f32_16x16x32_bf16 v[66:69], v[178:181], v[240:243], v[66:69]
	s_barrier
	s_add_i32 s14, s36, s18
	v_lshl_add_u64 v[168:169], v[168:169], 0, s[4:5]
	s_mov_b32 m0, s14
	ds_read_b128 v[182:185], v147 offset:49152
	ds_read_b128 v[186:189], v147 offset:50176
	ds_read_b128 v[190:193], v147 offset:51200
	ds_read_b128 v[194:197], v147 offset:52224
	ds_read_b128 v[198:201], v147 offset:53248
	ds_read_b128 v[202:205], v147 offset:54272
	ds_read_b128 v[236:239], v147 offset:55296
	ds_read_b128 v[240:243], v147 offset:56320
	global_load_lds_dwordx4 v[168:169], off
	s_add_i32 m0, s14, 0x2000
	s_add_u32 s12, s12, 0x40080
	v_lshl_add_u64 v[168:169], v[206:207], 0, s[4:5]
	s_addc_u32 s13, s13, 0
	s_add_i32 s14, s37, s18
	global_load_lds_dwordx4 v[168:169], off
	v_lshl_add_u64 v[168:169], s[12:13], 0, v[0:1]
	s_mov_b32 m0, s14
	s_nop 0
	global_load_lds_dwordx4 v[168:169], off
	v_lshl_add_u64 v[168:169], s[12:13], 0, v[130:131]
	s_add_i32 m0, s14, 0x2000
	s_nop 0
	global_load_lds_dwordx4 v[168:169], off
	v_lshl_add_u64 v[168:169], v[244:245], 0, s[4:5]
	s_mov_b32 m0, s70
	s_nop 0
	global_load_lds_dwordx4 v[168:169], off
	v_lshl_add_u64 v[168:169], v[246:247], 0, s[4:5]
	s_mov_b32 m0, s71
	s_nop 0
	global_load_lds_dwordx4 v[168:169], off
	s_waitcnt vmcnt(8)
	s_waitcnt lgkmcnt(0)
	s_barrier
	s_waitcnt lgkmcnt(0)
	v_mfma_f32_16x16x32_bf16 v[62:65], v[140:143], v[182:185], v[62:65]
	v_mfma_f32_16x16x32_bf16 v[58:61], v[152:155], v[182:185], v[58:61]
	v_mfma_f32_16x16x32_bf16 v[46:49], v[140:143], v[190:193], v[46:49]
	v_mfma_f32_16x16x32_bf16 v[42:45], v[152:155], v[190:193], v[42:45]
	v_mfma_f32_16x16x32_bf16 v[30:33], v[140:143], v[198:201], v[30:33]
	v_mfma_f32_16x16x32_bf16 v[26:29], v[152:155], v[198:201], v[26:29]
	v_mfma_f32_16x16x32_bf16 v[14:17], v[140:143], v[236:239], v[14:17]
	v_mfma_f32_16x16x32_bf16 v[10:13], v[152:155], v[236:239], v[10:13]
	v_mfma_f32_16x16x32_bf16 v[62:65], v[148:151], v[186:189], v[62:65]
	v_mfma_f32_16x16x32_bf16 v[58:61], v[156:159], v[186:189], v[58:61]
	v_mfma_f32_16x16x32_bf16 v[46:49], v[148:151], v[194:197], v[46:49]
	v_mfma_f32_16x16x32_bf16 v[42:45], v[156:159], v[194:197], v[42:45]
	v_mfma_f32_16x16x32_bf16 v[30:33], v[148:151], v[202:205], v[30:33]
	v_mfma_f32_16x16x32_bf16 v[26:29], v[156:159], v[202:205], v[26:29]
	v_mfma_f32_16x16x32_bf16 v[14:17], v[148:151], v[240:243], v[14:17]
	v_mfma_f32_16x16x32_bf16 v[10:13], v[156:159], v[240:243], v[10:13]
	v_mfma_f32_16x16x32_bf16 v[54:57], v[160:163], v[182:185], v[54:57]
	v_mfma_f32_16x16x32_bf16 v[50:53], v[174:177], v[182:185], v[50:53]
	v_mfma_f32_16x16x32_bf16 v[38:41], v[160:163], v[190:193], v[38:41]
	v_mfma_f32_16x16x32_bf16 v[34:37], v[174:177], v[190:193], v[34:37]
	v_mfma_f32_16x16x32_bf16 v[22:25], v[160:163], v[198:201], v[22:25]
	v_mfma_f32_16x16x32_bf16 v[18:21], v[174:177], v[198:201], v[18:21]
	v_mfma_f32_16x16x32_bf16 v[6:9], v[160:163], v[236:239], v[6:9]
	v_mfma_f32_16x16x32_bf16 v[2:5], v[174:177], v[236:239], v[2:5]
	v_mfma_f32_16x16x32_bf16 v[54:57], v[164:167], v[186:189], v[54:57]
	v_mfma_f32_16x16x32_bf16 v[50:53], v[178:181], v[186:189], v[50:53]
	v_mfma_f32_16x16x32_bf16 v[38:41], v[164:167], v[194:197], v[38:41]
	v_mfma_f32_16x16x32_bf16 v[34:37], v[178:181], v[194:197], v[34:37]
	v_mfma_f32_16x16x32_bf16 v[22:25], v[164:167], v[202:205], v[22:25]
	v_mfma_f32_16x16x32_bf16 v[18:21], v[178:181], v[202:205], v[18:21]
	v_mfma_f32_16x16x32_bf16 v[6:9], v[164:167], v[240:243], v[6:9]
	v_mfma_f32_16x16x32_bf16 v[2:5], v[178:181], v[240:243], v[2:5]
	s_barrier
	s_add_i32 s78, s78, 2
	s_add_u32 s10, s10, 0x100
	s_addc_u32 s11, s11, 0
	s_add_u32 s49, s49, 0x100
	s_addc_u32 s77, s77, 0
	s_cmp_gt_u32 s78, 13
	s_cbranch_scc0 .LBB0_437
	s_setprio 0
	s_and_b64 vcc, exec, s[6:7]
	s_cbranch_vccz .LBB0_440
	s_barrier

.LBB0_492:
	s_ashr_i32 s51, s50, 31
	s_lshl_b64 s[18:19], s[50:51], 19
	s_add_u32 s52, s20, s18
	s_addc_u32 s53, s39, s19
	s_and_b64 s[18:19], s[42:43], exec
	s_cselect_b32 s11, s53, s15
	s_cselect_b32 s13, s52, s14
	s_waitcnt lgkmcnt(0)
	s_ashr_i32 s49, s48, 31
	s_lshl_b64 s[18:19], s[48:49], 19
	s_add_u32 s54, s34, s18
	s_addc_u32 s55, s70, s19
	s_and_b64 s[18:19], s[42:43], exec
	s_cselect_b32 s40, s55, s17
	s_cselect_b32 s41, s54, s16
	s_add_u32 s14, s14, 0x40080
	s_addc_u32 s15, s15, 0
	s_add_u32 s44, s16, 0x100
	v_mov_b32_e32 v2, 0
	s_addc_u32 s45, s17, 0
	s_mov_b32 s46, -2
	v_mov_b32_e32 v3, v2
	v_pk_mov_b32 v[4:5], v[2:3], v[2:3] op_sel:[0,1]
	v_pk_mov_b32 v[6:7], v[2:3], v[2:3] op_sel:[0,1]
	v_pk_mov_b32 v[8:9], v[2:3], v[2:3] op_sel:[0,1]
	v_pk_mov_b32 v[18:19], v[2:3], v[2:3] op_sel:[0,1]
	v_pk_mov_b32 v[20:21], v[2:3], v[2:3] op_sel:[0,1]
	v_pk_mov_b32 v[22:23], v[2:3], v[2:3] op_sel:[0,1]
	v_pk_mov_b32 v[24:25], v[2:3], v[2:3] op_sel:[0,1]
	v_pk_mov_b32 v[34:35], v[2:3], v[2:3] op_sel:[0,1]
	v_pk_mov_b32 v[36:37], v[2:3], v[2:3] op_sel:[0,1]
	v_pk_mov_b32 v[38:39], v[2:3], v[2:3] op_sel:[0,1]
	v_pk_mov_b32 v[40:41], v[2:3], v[2:3] op_sel:[0,1]
	v_pk_mov_b32 v[50:51], v[2:3], v[2:3] op_sel:[0,1]
	v_pk_mov_b32 v[52:53], v[2:3], v[2:3] op_sel:[0,1]
	v_pk_mov_b32 v[54:55], v[2:3], v[2:3] op_sel:[0,1]
	v_pk_mov_b32 v[56:57], v[2:3], v[2:3] op_sel:[0,1]
	v_pk_mov_b32 v[10:11], v[2:3], v[2:3] op_sel:[0,1]
	v_pk_mov_b32 v[12:13], v[2:3], v[2:3] op_sel:[0,1]
	v_pk_mov_b32 v[14:15], v[2:3], v[2:3] op_sel:[0,1]
	v_pk_mov_b32 v[16:17], v[2:3], v[2:3] op_sel:[0,1]
	v_pk_mov_b32 v[26:27], v[2:3], v[2:3] op_sel:[0,1]
	v_pk_mov_b32 v[28:29], v[2:3], v[2:3] op_sel:[0,1]
	v_pk_mov_b32 v[30:31], v[2:3], v[2:3] op_sel:[0,1]
	v_pk_mov_b32 v[32:33], v[2:3], v[2:3] op_sel:[0,1]
	v_pk_mov_b32 v[42:43], v[2:3], v[2:3] op_sel:[0,1]
	v_pk_mov_b32 v[44:45], v[2:3], v[2:3] op_sel:[0,1]
	v_pk_mov_b32 v[46:47], v[2:3], v[2:3] op_sel:[0,1]
	v_pk_mov_b32 v[48:49], v[2:3], v[2:3] op_sel:[0,1]
	v_pk_mov_b32 v[58:59], v[2:3], v[2:3] op_sel:[0,1]
	v_pk_mov_b32 v[60:61], v[2:3], v[2:3] op_sel:[0,1]
	v_pk_mov_b32 v[62:63], v[2:3], v[2:3] op_sel:[0,1]
	v_pk_mov_b32 v[64:65], v[2:3], v[2:3] op_sel:[0,1]
	v_pk_mov_b32 v[66:67], v[2:3], v[2:3] op_sel:[0,1]
	v_pk_mov_b32 v[68:69], v[2:3], v[2:3] op_sel:[0,1]
	v_pk_mov_b32 v[70:71], v[2:3], v[2:3] op_sel:[0,1]
	v_pk_mov_b32 v[72:73], v[2:3], v[2:3] op_sel:[0,1]
	v_pk_mov_b32 v[82:83], v[2:3], v[2:3] op_sel:[0,1]
	v_pk_mov_b32 v[84:85], v[2:3], v[2:3] op_sel:[0,1]
	v_pk_mov_b32 v[86:87], v[2:3], v[2:3] op_sel:[0,1]
	v_pk_mov_b32 v[88:89], v[2:3], v[2:3] op_sel:[0,1]
	v_pk_mov_b32 v[98:99], v[2:3], v[2:3] op_sel:[0,1]
	v_pk_mov_b32 v[100:101], v[2:3], v[2:3] op_sel:[0,1]
	v_pk_mov_b32 v[102:103], v[2:3], v[2:3] op_sel:[0,1]
	v_pk_mov_b32 v[104:105], v[2:3], v[2:3] op_sel:[0,1]
	v_pk_mov_b32 v[114:115], v[2:3], v[2:3] op_sel:[0,1]
	v_pk_mov_b32 v[116:117], v[2:3], v[2:3] op_sel:[0,1]
	v_pk_mov_b32 v[118:119], v[2:3], v[2:3] op_sel:[0,1]
	v_pk_mov_b32 v[120:121], v[2:3], v[2:3] op_sel:[0,1]
	v_pk_mov_b32 v[74:75], v[2:3], v[2:3] op_sel:[0,1]
	v_pk_mov_b32 v[76:77], v[2:3], v[2:3] op_sel:[0,1]
	v_pk_mov_b32 v[78:79], v[2:3], v[2:3] op_sel:[0,1]
	v_pk_mov_b32 v[80:81], v[2:3], v[2:3] op_sel:[0,1]
	v_pk_mov_b32 v[90:91], v[2:3], v[2:3] op_sel:[0,1]
	v_pk_mov_b32 v[92:93], v[2:3], v[2:3] op_sel:[0,1]
	v_pk_mov_b32 v[94:95], v[2:3], v[2:3] op_sel:[0,1]
	v_pk_mov_b32 v[96:97], v[2:3], v[2:3] op_sel:[0,1]
	v_pk_mov_b32 v[106:107], v[2:3], v[2:3] op_sel:[0,1]
	v_pk_mov_b32 v[108:109], v[2:3], v[2:3] op_sel:[0,1]
	v_pk_mov_b32 v[110:111], v[2:3], v[2:3] op_sel:[0,1]
	v_pk_mov_b32 v[112:113], v[2:3], v[2:3] op_sel:[0,1]
	v_pk_mov_b32 v[122:123], v[2:3], v[2:3] op_sel:[0,1]
	v_pk_mov_b32 v[124:125], v[2:3], v[2:3] op_sel:[0,1]
	v_pk_mov_b32 v[126:127], v[2:3], v[2:3] op_sel:[0,1]
	v_pk_mov_b32 v[128:129], v[2:3], v[2:3] op_sel:[0,1]
	v_readfirstlane_b32 s98, v208
	s_bitcmp1_b32 s98, 8
	s_cbranch_scc0 .Lsp_493
	s_setprio 1
.Lsp_493:
.LBB0_493:
	s_add_u32 s16, s14, 0xfffc0080
	s_addc_u32 s17, s15, -1
	s_add_i32 s36, 0, 0x10000
	s_cmp_eq_u32 s46, 12
	s_cselect_b32 s19, s11, s17
	s_cselect_b32 s18, s13, s16
	s_cselect_b32 s17, s40, s45
	s_cselect_b32 s16, s41, s44
	s_add_i32 s37, 0, 0x14000
	v_add_u32_e32 v156, s36, v145
	v_add_u32_e32 v168, s37, v145
	ds_read_b128 v[140:143], v156
	ds_read_b128 v[148:151], v156 offset:1024
	ds_read_b128 v[152:155], v156 offset:2048
	ds_read_b128 v[156:159], v156 offset:3072
	ds_read_b128 v[160:163], v168
	ds_read_b128 v[164:167], v168 offset:1024
	ds_read_b128 v[174:177], v168 offset:2048
	ds_read_b128 v[178:181], v168 offset:3072
	v_lshl_add_u64 v[168:169], s[14:15], 0, v[136:137]
	s_add_i32 m0, s74, 0xc000
	ds_read_b128 v[182:185], v147
	ds_read_b128 v[186:189], v147 offset:1024
	ds_read_b128 v[190:193], v147 offset:2048
	ds_read_b128 v[194:197], v147 offset:3072
	ds_read_b128 v[198:201], v147 offset:4096
	ds_read_b128 v[202:205], v147 offset:5120
	ds_read_b128 v[236:239], v147 offset:6144
	ds_read_b128 v[240:243], v147 offset:7168
	global_load_lds_dwordx4 v[168:169], off
	v_lshl_add_u64 v[168:169], s[14:15], 0, v[138:139]
	s_add_i32 m0, s74, 0xe000
	s_nop 0
	global_load_lds_dwordx4 v[168:169], off
	s_waitcnt vmcnt(8)
	s_waitcnt lgkmcnt(0)
	s_barrier
	s_waitcnt lgkmcnt(0)
	v_mfma_f32_16x16x32_bf16 v[126:129], v[140:143], v[182:185], v[126:129]
	v_mfma_f32_16x16x32_bf16 v[122:125], v[152:155], v[182:185], v[122:125]
	v_mfma_f32_16x16x32_bf16 v[110:113], v[140:143], v[190:193], v[110:113]
	v_mfma_f32_16x16x32_bf16 v[106:109], v[152:155], v[190:193], v[106:109]
	v_mfma_f32_16x16x32_bf16 v[94:97], v[140:143], v[198:201], v[94:97]
	v_mfma_f32_16x16x32_bf16 v[90:93], v[152:155], v[198:201], v[90:93]
	v_mfma_f32_16x16x32_bf16 v[78:81], v[140:143], v[236:239], v[78:81]
	v_mfma_f32_16x16x32_bf16 v[74:77], v[152:155], v[236:239], v[74:77]
	v_mfma_f32_16x16x32_bf16 v[126:129], v[148:151], v[186:189], v[126:129]
	v_mfma_f32_16x16x32_bf16 v[122:125], v[156:159], v[186:189], v[122:125]
	v_mfma_f32_16x16x32_bf16 v[110:113], v[148:151], v[194:197], v[110:113]
	v_mfma_f32_16x16x32_bf16 v[106:109], v[156:159], v[194:197], v[106:109]
	v_mfma_f32_16x16x32_bf16 v[94:97], v[148:151], v[202:205], v[94:97]
	v_mfma_f32_16x16x32_bf16 v[90:93], v[156:159], v[202:205], v[90:93]
	v_mfma_f32_16x16x32_bf16 v[78:81], v[148:151], v[240:243], v[78:81]
	v_mfma_f32_16x16x32_bf16 v[74:77], v[156:159], v[240:243], v[74:77]
	v_mfma_f32_16x16x32_bf16 v[118:121], v[160:163], v[182:185], v[118:121]
	v_mfma_f32_16x16x32_bf16 v[114:117], v[174:177], v[182:185], v[114:117]
	v_mfma_f32_16x16x32_bf16 v[102:105], v[160:163], v[190:193], v[102:105]
	v_mfma_f32_16x16x32_bf16 v[98:101], v[174:177], v[190:193], v[98:101]
	v_mfma_f32_16x16x32_bf16 v[86:89], v[160:163], v[198:201], v[86:89]
	v_mfma_f32_16x16x32_bf16 v[82:85], v[174:177], v[198:201], v[82:85]
	v_mfma_f32_16x16x32_bf16 v[70:73], v[160:163], v[236:239], v[70:73]
	v_mfma_f32_16x16x32_bf16 v[66:69], v[174:177], v[236:239], v[66:69]
	v_mfma_f32_16x16x32_bf16 v[118:121], v[164:167], v[186:189], v[118:121]
	v_mfma_f32_16x16x32_bf16 v[114:117], v[178:181], v[186:189], v[114:117]
	v_mfma_f32_16x16x32_bf16 v[102:105], v[164:167], v[194:197], v[102:105]
	v_mfma_f32_16x16x32_bf16 v[98:101], v[178:181], v[194:197], v[98:101]
	v_mfma_f32_16x16x32_bf16 v[86:89], v[164:167], v[202:205], v[86:89]
	v_mfma_f32_16x16x32_bf16 v[82:85], v[178:181], v[202:205], v[82:85]
	v_mfma_f32_16x16x32_bf16 v[70:73], v[164:167], v[240:243], v[70:73]
	v_mfma_f32_16x16x32_bf16 v[66:69], v[178:181], v[240:243], v[66:69]
	s_barrier
	s_add_i32 s36, s36, s71
	v_lshl_add_u64 v[168:169], s[16:17], 0, v[0:1]
	s_mov_b32 m0, s36
	ds_read_b128 v[182:185], v147 offset:16384
	ds_read_b128 v[186:189], v147 offset:17408
	ds_read_b128 v[190:193], v147 offset:18432
	ds_read_b128 v[194:197], v147 offset:19456
	ds_read_b128 v[198:201], v147 offset:20480
	ds_read_b128 v[202:205], v147 offset:21504
	ds_read_b128 v[236:239], v147 offset:22528
	ds_read_b128 v[240:243], v147 offset:23552
	global_load_lds_dwordx4 v[168:169], off
	s_add_i32 m0, s36, 0x2000
	s_add_u32 s88, s16, 0x40000
	v_lshl_add_u64 v[206:207], s[16:17], 0, v[134:135]
	s_addc_u32 s89, s17, 0
	s_add_i32 s36, s37, s71
	global_load_lds_dwordx4 v[206:207], off
	v_lshl_add_u64 v[244:245], s[88:89], 0, v[0:1]
	s_mov_b32 m0, s36
	v_lshl_add_u64 v[246:247], s[18:19], 0, v[132:133]
	global_load_lds_dwordx4 v[244:245], off
	v_lshl_add_u64 v[244:245], s[88:89], 0, v[134:135]
	s_add_i32 m0, s36, 0x2000
	s_nop 0
	global_load_lds_dwordx4 v[244:245], off
	v_lshl_add_u64 v[244:245], s[18:19], 0, v[130:131]
	s_mov_b32 m0, s74
	s_nop 0
	global_load_lds_dwordx4 v[244:245], off
	s_mov_b32 m0, s75
	s_nop 0
	global_load_lds_dwordx4 v[246:247], off
	s_waitcnt vmcnt(8)
	s_waitcnt lgkmcnt(0)
	s_barrier
	s_waitcnt lgkmcnt(0)
	v_mfma_f32_16x16x32_bf16 v[62:65], v[140:143], v[182:185], v[62:65]
	v_mfma_f32_16x16x32_bf16 v[58:61], v[152:155], v[182:185], v[58:61]
	v_mfma_f32_16x16x32_bf16 v[46:49], v[140:143], v[190:193], v[46:49]
	v_mfma_f32_16x16x32_bf16 v[42:45], v[152:155], v[190:193], v[42:45]
	v_mfma_f32_16x16x32_bf16 v[30:33], v[140:143], v[198:201], v[30:33]
	v_mfma_f32_16x16x32_bf16 v[26:29], v[152:155], v[198:201], v[26:29]
	v_mfma_f32_16x16x32_bf16 v[14:17], v[140:143], v[236:239], v[14:17]
	v_mfma_f32_16x16x32_bf16 v[10:13], v[152:155], v[236:239], v[10:13]
	v_mfma_f32_16x16x32_bf16 v[62:65], v[148:151], v[186:189], v[62:65]
	v_mfma_f32_16x16x32_bf16 v[58:61], v[156:159], v[186:189], v[58:61]
	v_mfma_f32_16x16x32_bf16 v[46:49], v[148:151], v[194:197], v[46:49]
	v_mfma_f32_16x16x32_bf16 v[42:45], v[156:159], v[194:197], v[42:45]
	v_mfma_f32_16x16x32_bf16 v[30:33], v[148:151], v[202:205], v[30:33]
	v_mfma_f32_16x16x32_bf16 v[26:29], v[156:159], v[202:205], v[26:29]
	v_mfma_f32_16x16x32_bf16 v[14:17], v[148:151], v[240:243], v[14:17]
	v_mfma_f32_16x16x32_bf16 v[10:13], v[156:159], v[240:243], v[10:13]
	v_mfma_f32_16x16x32_bf16 v[54:57], v[160:163], v[182:185], v[54:57]
	v_mfma_f32_16x16x32_bf16 v[50:53], v[174:177], v[182:185], v[50:53]
	v_mfma_f32_16x16x32_bf16 v[38:41], v[160:163], v[190:193], v[38:41]
	v_mfma_f32_16x16x32_bf16 v[34:37], v[174:177], v[190:193], v[34:37]
	v_mfma_f32_16x16x32_bf16 v[22:25], v[160:163], v[198:201], v[22:25]
	v_mfma_f32_16x16x32_bf16 v[18:21], v[174:177], v[198:201], v[18:21]
	v_mfma_f32_16x16x32_bf16 v[6:9], v[160:163], v[236:239], v[6:9]
	v_mfma_f32_16x16x32_bf16 v[2:5], v[174:177], v[236:239], v[2:5]
	v_mfma_f32_16x16x32_bf16 v[54:57], v[164:167], v[186:189], v[54:57]
	v_mfma_f32_16x16x32_bf16 v[50:53], v[178:181], v[186:189], v[50:53]
	v_mfma_f32_16x16x32_bf16 v[38:41], v[164:167], v[194:197], v[38:41]
	v_mfma_f32_16x16x32_bf16 v[34:37], v[178:181], v[194:197], v[34:37]
	v_mfma_f32_16x16x32_bf16 v[22:25], v[164:167], v[202:205], v[22:25]
	v_mfma_f32_16x16x32_bf16 v[18:21], v[178:181], v[202:205], v[18:21]
	v_mfma_f32_16x16x32_bf16 v[6:9], v[164:167], v[240:243], v[6:9]
	v_mfma_f32_16x16x32_bf16 v[2:5], v[178:181], v[240:243], v[2:5]
	s_barrier
	s_add_i32 s36, 0, 0x18000
	s_add_i32 s37, 0, 0x1c000
	v_add_u32_e32 v156, s36, v145
	v_add_u32_e32 v178, s37, v145
	ds_read_b128 v[140:143], v156
	ds_read_b128 v[148:151], v156 offset:1024
	ds_read_b128 v[152:155], v156 offset:2048
	ds_read_b128 v[156:159], v156 offset:3072
	ds_read_b128 v[160:163], v178
	ds_read_b128 v[164:167], v178 offset:1024
	ds_read_b128 v[174:177], v178 offset:2048
	ds_read_b128 v[178:181], v178 offset:3072
	s_add_u32 s18, s18, 0x40000
	s_addc_u32 s19, s19, 0
	s_mov_b32 m0, s77
	v_lshl_add_u64 v[248:249], s[18:19], 0, v[130:131]
	ds_read_b128 v[182:185], v147 offset:32768
	ds_read_b128 v[186:189], v147 offset:33792
	ds_read_b128 v[190:193], v147 offset:34816
	ds_read_b128 v[194:197], v147 offset:35840
	ds_read_b128 v[198:201], v147 offset:36864
	ds_read_b128 v[202:205], v147 offset:37888
	ds_read_b128 v[236:239], v147 offset:38912
	ds_read_b128 v[240:243], v147 offset:39936
	global_load_lds_dwordx4 v[248:249], off
	v_lshl_add_u64 v[248:249], s[18:19], 0, v[132:133]
	s_mov_b32 m0, s78
	s_nop 0
	global_load_lds_dwordx4 v[248:249], off
	s_waitcnt vmcnt(8)
	s_waitcnt lgkmcnt(0)
	s_barrier
	s_waitcnt lgkmcnt(0)
	v_mfma_f32_16x16x32_bf16 v[126:129], v[140:143], v[182:185], v[126:129]
	v_mfma_f32_16x16x32_bf16 v[122:125], v[152:155], v[182:185], v[122:125]
	v_mfma_f32_16x16x32_bf16 v[110:113], v[140:143], v[190:193], v[110:113]
	v_mfma_f32_16x16x32_bf16 v[106:109], v[152:155], v[190:193], v[106:109]
	v_mfma_f32_16x16x32_bf16 v[94:97], v[140:143], v[198:201], v[94:97]
	v_mfma_f32_16x16x32_bf16 v[90:93], v[152:155], v[198:201], v[90:93]
	v_mfma_f32_16x16x32_bf16 v[78:81], v[140:143], v[236:239], v[78:81]
	v_mfma_f32_16x16x32_bf16 v[74:77], v[152:155], v[236:239], v[74:77]
	v_mfma_f32_16x16x32_bf16 v[126:129], v[148:151], v[186:189], v[126:129]
	v_mfma_f32_16x16x32_bf16 v[122:125], v[156:159], v[186:189], v[122:125]
	v_mfma_f32_16x16x32_bf16 v[110:113], v[148:151], v[194:197], v[110:113]
	v_mfma_f32_16x16x32_bf16 v[106:109], v[156:159], v[194:197], v[106:109]
	v_mfma_f32_16x16x32_bf16 v[94:97], v[148:151], v[202:205], v[94:97]
	v_mfma_f32_16x16x32_bf16 v[90:93], v[156:159], v[202:205], v[90:93]
	v_mfma_f32_16x16x32_bf16 v[78:81], v[148:151], v[240:243], v[78:81]
	v_mfma_f32_16x16x32_bf16 v[74:77], v[156:159], v[240:243], v[74:77]
	v_mfma_f32_16x16x32_bf16 v[118:121], v[160:163], v[182:185], v[118:121]
	v_mfma_f32_16x16x32_bf16 v[114:117], v[174:177], v[182:185], v[114:117]
	v_mfma_f32_16x16x32_bf16 v[102:105], v[160:163], v[190:193], v[102:105]
	v_mfma_f32_16x16x32_bf16 v[98:101], v[174:177], v[190:193], v[98:101]
	v_mfma_f32_16x16x32_bf16 v[86:89], v[160:163], v[198:201], v[86:89]
	v_mfma_f32_16x16x32_bf16 v[82:85], v[174:177], v[198:201], v[82:85]
	v_mfma_f32_16x16x32_bf16 v[70:73], v[160:163], v[236:239], v[70:73]
	v_mfma_f32_16x16x32_bf16 v[66:69], v[174:177], v[236:239], v[66:69]
	v_mfma_f32_16x16x32_bf16 v[118:121], v[164:167], v[186:189], v[118:121]
	v_mfma_f32_16x16x32_bf16 v[114:117], v[178:181], v[186:189], v[114:117]
	v_mfma_f32_16x16x32_bf16 v[102:105], v[164:167], v[194:197], v[102:105]
	v_mfma_f32_16x16x32_bf16 v[98:101], v[178:181], v[194:197], v[98:101]
	v_mfma_f32_16x16x32_bf16 v[86:89], v[164:167], v[202:205], v[86:89]
	v_mfma_f32_16x16x32_bf16 v[82:85], v[178:181], v[202:205], v[82:85]
	v_mfma_f32_16x16x32_bf16 v[70:73], v[164:167], v[240:243], v[70:73]
	v_mfma_f32_16x16x32_bf16 v[66:69], v[178:181], v[240:243], v[66:69]
	s_barrier
	s_add_i32 s18, s36, s71
	v_lshl_add_u64 v[168:169], v[168:169], 0, s[4:5]
	s_mov_b32 m0, s18
	ds_read_b128 v[182:185], v147 offset:49152
	ds_read_b128 v[186:189], v147 offset:50176
	ds_read_b128 v[190:193], v147 offset:51200
	ds_read_b128 v[194:197], v147 offset:52224
	ds_read_b128 v[198:201], v147 offset:53248
	ds_read_b128 v[202:205], v147 offset:54272
	ds_read_b128 v[236:239], v147 offset:55296
	ds_read_b128 v[240:243], v147 offset:56320
	global_load_lds_dwordx4 v[168:169], off
	s_add_i32 m0, s18, 0x2000
	s_add_u32 s16, s16, 0x40080
	v_lshl_add_u64 v[168:169], v[206:207], 0, s[4:5]
	s_addc_u32 s17, s17, 0
	s_add_i32 s18, s37, s71
	global_load_lds_dwordx4 v[168:169], off
	v_lshl_add_u64 v[168:169], s[16:17], 0, v[0:1]
	s_mov_b32 m0, s18
	s_nop 0
	global_load_lds_dwordx4 v[168:169], off
	v_lshl_add_u64 v[168:169], s[16:17], 0, v[134:135]
	s_add_i32 m0, s18, 0x2000
	s_nop 0
	global_load_lds_dwordx4 v[168:169], off
	v_lshl_add_u64 v[168:169], v[244:245], 0, s[4:5]
	s_mov_b32 m0, s79
	s_nop 0
	global_load_lds_dwordx4 v[168:169], off
	v_lshl_add_u64 v[168:169], v[246:247], 0, s[4:5]
	s_mov_b32 m0, s82
	s_nop 0
	global_load_lds_dwordx4 v[168:169], off
	s_waitcnt vmcnt(8)
	s_waitcnt lgkmcnt(0)
	s_barrier
	s_waitcnt lgkmcnt(0)
	v_mfma_f32_16x16x32_bf16 v[62:65], v[140:143], v[182:185], v[62:65]
	v_mfma_f32_16x16x32_bf16 v[58:61], v[152:155], v[182:185], v[58:61]
	v_mfma_f32_16x16x32_bf16 v[46:49], v[140:143], v[190:193], v[46:49]
	v_mfma_f32_16x16x32_bf16 v[42:45], v[152:155], v[190:193], v[42:45]
	v_mfma_f32_16x16x32_bf16 v[30:33], v[140:143], v[198:201], v[30:33]
	v_mfma_f32_16x16x32_bf16 v[26:29], v[152:155], v[198:201], v[26:29]
	v_mfma_f32_16x16x32_bf16 v[14:17], v[140:143], v[236:239], v[14:17]
	v_mfma_f32_16x16x32_bf16 v[10:13], v[152:155], v[236:239], v[10:13]
	v_mfma_f32_16x16x32_bf16 v[62:65], v[148:151], v[186:189], v[62:65]
	v_mfma_f32_16x16x32_bf16 v[58:61], v[156:159], v[186:189], v[58:61]
	v_mfma_f32_16x16x32_bf16 v[46:49], v[148:151], v[194:197], v[46:49]
	v_mfma_f32_16x16x32_bf16 v[42:45], v[156:159], v[194:197], v[42:45]
	v_mfma_f32_16x16x32_bf16 v[30:33], v[148:151], v[202:205], v[30:33]
	v_mfma_f32_16x16x32_bf16 v[26:29], v[156:159], v[202:205], v[26:29]
	v_mfma_f32_16x16x32_bf16 v[14:17], v[148:151], v[240:243], v[14:17]
	v_mfma_f32_16x16x32_bf16 v[10:13], v[156:159], v[240:243], v[10:13]
	v_mfma_f32_16x16x32_bf16 v[54:57], v[160:163], v[182:185], v[54:57]
	v_mfma_f32_16x16x32_bf16 v[50:53], v[174:177], v[182:185], v[50:53]
	v_mfma_f32_16x16x32_bf16 v[38:41], v[160:163], v[190:193], v[38:41]
	v_mfma_f32_16x16x32_bf16 v[34:37], v[174:177], v[190:193], v[34:37]
	v_mfma_f32_16x16x32_bf16 v[22:25], v[160:163], v[198:201], v[22:25]
	v_mfma_f32_16x16x32_bf16 v[18:21], v[174:177], v[198:201], v[18:21]
	v_mfma_f32_16x16x32_bf16 v[6:9], v[160:163], v[236:239], v[6:9]
	v_mfma_f32_16x16x32_bf16 v[2:5], v[174:177], v[236:239], v[2:5]
	v_mfma_f32_16x16x32_bf16 v[54:57], v[164:167], v[186:189], v[54:57]
	v_mfma_f32_16x16x32_bf16 v[50:53], v[178:181], v[186:189], v[50:53]
	v_mfma_f32_16x16x32_bf16 v[38:41], v[164:167], v[194:197], v[38:41]
	v_mfma_f32_16x16x32_bf16 v[34:37], v[178:181], v[194:197], v[34:37]
	v_mfma_f32_16x16x32_bf16 v[22:25], v[164:167], v[202:205], v[22:25]
	v_mfma_f32_16x16x32_bf16 v[18:21], v[178:181], v[202:205], v[18:21]
	v_mfma_f32_16x16x32_bf16 v[6:9], v[164:167], v[240:243], v[6:9]
	v_mfma_f32_16x16x32_bf16 v[2:5], v[178:181], v[240:243], v[2:5]
	s_barrier
	s_add_i32 s46, s46, 2
	s_add_u32 s14, s14, 0x100
	s_addc_u32 s15, s15, 0
	s_add_u32 s44, s44, 0x100
	s_addc_u32 s45, s45, 0
	s_cmp_gt_u32 s46, 13
	s_cbranch_scc0 .LBB0_493
	s_setprio 0
	s_and_b64 vcc, exec, s[8:9]
	s_cbranch_vccz .LBB0_496
	s_barrier
